# out-proj epilogue: residual register preload extended from 32 to 63 chain elements (batches of 16, counted vmcnt)
# baseline (speedup 1.0000x reference)
; DI int crow(int i, int h) { return (i & 3) + 8 * (i >> 2) + 4 * h; }
; DI const float* xrow(CP p, const Ptrs& w, int l, int tok) {
;   int b = tok / TPB, i = tok - b * TPB;
;   if (l == 0) return i < CTXL ? p.in[2] + (size_t)(b * CTXL + i) * DM : p.in[0] + (size_t)(b * 8192 + i - CTXL) * DM;
;   return i < CTXL ? w.xc1 + (size_t)(b * CTXL + i) * DM : p.out + (size_t)(b * 8192 + i - CTXL) * DM;
; DI void phase_out(CP p, const Ptrs& w, int l, bf16_t* sA, bf16_t* sB) {
;     ...
;         int col = n0 + wn * 64 + ni * 32 + r;
;         float gt = gate[col];
; #pragma unroll
;         for (int i = 0; i < 16; ++i) {
;           int ii = ib + wm * 64 + mi * 32 + crow(i, h);
;           const float* src = xrow(p, w, l, b * TPB + ii);
;           float* dstp = isctx ? w.xc1 + (size_t)(b * CTXL + ii) * DM : p.out + (size_t)(b * 8192 + ii - CTXL) * DM;
;           dstp[col] = src[col] + gt * acc[mi][ni][i];
.LBB0_967:
	s_lshl_b32 s10, s39, 13
	s_addk_i32 s10, 0xff00
	s_lshl_b32 s11, s39, 8
	v_ashrrev_i32_e32 v67, 31, v66
	s_and_b64 s[4:5], s[4:5], exec
	v_lshlrev_b64 v[66:67], 13, v[66:67]
	s_cselect_b32 s39, s11, s10
	v_lshl_add_u64 v[70:71], v[70:71], 0, v[66:67]
	v_add_u32_e32 v66, s39, v72
	v_ashrrev_i32_e32 v67, 31, v66
	s_cselect_b32 s5, s13, s77
	s_cselect_b32 s4, s12, s76
	v_lshlrev_b64 v[66:67], 13, v[66:67]
	v_lshl_add_u64 v[72:73], s[4:5], 0, v[66:67]
	v_lshlrev_b64 v[66:67], 2, v[64:65]
	v_lshl_add_u64 v[70:71], v[70:71], 0, v[66:67]
	s_nop 0
	v_readfirstlane_b32 s100, v70
	v_readfirstlane_b32 s101, v71
	v_mbcnt_lo_u32_b32 v168, -1, 0
	v_mbcnt_hi_u32_b32 v168, -1, v168
	v_lshlrev_b32_e32 v168, 13, v168
	s_nop 2
	global_load_dword v169, v168, s[100:101]
	global_load_dword v169, v168, s[100:101] offset:128
	v_subrev_u32_e32 v170, s100, v70
	global_load_dword v194, v170, s[100:101]
	v_add_u32_e32 v171, 0x2000, v170
	global_load_dword v195, v171, s[100:101]
	v_add_u32_e32 v171, 0x4000, v170
	global_load_dword v196, v171, s[100:101]
	v_add_u32_e32 v171, 0x6000, v170
	global_load_dword v197, v171, s[100:101]
	v_add_u32_e32 v171, 0x10000, v170
	global_load_dword v198, v171, s[100:101]
	v_add_u32_e32 v171, 0x12000, v170
	global_load_dword v199, v171, s[100:101]
	v_add_u32_e32 v171, 0x14000, v170
	global_load_dword v200, v171, s[100:101]
	v_add_u32_e32 v171, 0x16000, v170
	global_load_dword v201, v171, s[100:101]
	v_add_u32_e32 v171, 0x20000, v170
	global_load_dword v202, v171, s[100:101]
	v_add_u32_e32 v171, 0x22000, v170
	global_load_dword v203, v171, s[100:101]
	v_add_u32_e32 v171, 0x24000, v170
	global_load_dword v204, v171, s[100:101]
	v_add_u32_e32 v171, 0x26000, v170
	global_load_dword v205, v171, s[100:101]
	v_add_u32_e32 v171, 0x30000, v170
	global_load_dword v206, v171, s[100:101]
	v_add_u32_e32 v171, 0x32000, v170
	global_load_dword v207, v171, s[100:101]
	v_add_u32_e32 v171, 0x34000, v170
	global_load_dword v208, v171, s[100:101]
	v_add_u32_e32 v171, 0x36000, v170
	global_load_dword v209, v171, s[100:101]
	v_add_u32_e32 v171, 0x80, v170
	global_load_dword v210, v171, s[100:101]
	v_add_u32_e32 v171, 0x2080, v170
	global_load_dword v211, v171, s[100:101]
	v_add_u32_e32 v171, 0x4080, v170
	global_load_dword v212, v171, s[100:101]
	v_add_u32_e32 v171, 0x6080, v170
	global_load_dword v213, v171, s[100:101]
	v_add_u32_e32 v171, 0x10080, v170
	global_load_dword v172, v171, s[100:101]
	v_add_u32_e32 v171, 0x12080, v170
	global_load_dword v173, v171, s[100:101]
	v_add_u32_e32 v171, 0x14080, v170
	global_load_dword v174, v171, s[100:101]
	v_add_u32_e32 v171, 0x16080, v170
	global_load_dword v175, v171, s[100:101]
	v_add_u32_e32 v171, 0x20080, v170
	global_load_dword v176, v171, s[100:101]
	v_add_u32_e32 v171, 0x22080, v170
	global_load_dword v177, v171, s[100:101]
	v_add_u32_e32 v171, 0x24080, v170
	global_load_dword v178, v171, s[100:101]
	v_add_u32_e32 v171, 0x26080, v170
	global_load_dword v179, v171, s[100:101]
	v_add_u32_e32 v171, 0x30080, v170
	global_load_dword v132, v171, s[100:101]
	v_add_u32_e32 v171, 0x32080, v170
	global_load_dword v133, v171, s[100:101]
	v_add_u32_e32 v171, 0x34080, v170
	global_load_dword v134, v171, s[100:101]
	v_add_u32_e32 v171, 0x36080, v170
	global_load_dword v135, v171, s[100:101]
	v_lshl_add_u64 v[70:71], v[72:73], 0, v[66:67]
	v_readlane_b32 s46, v254, 54
	v_readlane_b32 s47, v254, 55
	s_mov_b64 s[10:11], -1
	s_andn2_b64 vcc, exec, s[46:47]
	s_waitcnt vmcnt(31)
	v_fma_f32 v74, v48, v90, v194
	v_or_b32_e32 v48, v92, v167
	v_add_u32_e32 v72, s38, v48
	v_mul_hi_i32 v73, v72, s0
	global_store_dword v[70:71], v74, off
	v_lshrrev_b32_e32 v74, 31, v73
	v_ashrrev_i32_e32 v73, 11, v73
	v_add_u32_e32 v95, v73, v74
	v_mad_i32_i24 v96, v95, s1, v72
	v_cndmask_b32_e64 v72, 0, 1, s[46:47]
	v_cmp_lt_i32_e64 s[44:45], s37, v96
	v_cmp_ne_u32_e64 s[40:41], 1, v72
	s_cbranch_vccnz .LBB0_973
	s_and_saveexec_b64 s[10:11], s[44:45]
	s_xor_b64 s[10:11], exec, s[10:11]
	v_lshlrev_b32_e32 v72, 13, v95
	s_movk_i32 s46, 0xff00
	v_add3_u32 v72, v72, v96, s46
	s_or_saveexec_b64 s[10:11], s[10:11]
	v_mov_b64_e32 v[74:75], s[76:77]
	s_xor_b64 exec, exec, s[10:11]
	v_lshl_add_u32 v72, v95, 8, v96
	v_mov_b64_e32 v[74:75], s[12:13]
	s_or_b64 exec, exec, s[10:11]
	s_mov_b64 s[10:11], 0

; DI int crow(int i, int h) { return (i & 3) + 8 * (i >> 2) + 4 * h; }
; DI void phase_out(CP p, const Ptrs& w, int l, bf16_t* sA, bf16_t* sB) {
;     ...
;         int col = n0 + wn * 64 + ni * 32 + r;
;         float gt = gate[col];
; #pragma unroll
;         for (int i = 0; i < 16; ++i) {
;           int ii = ib + wm * 64 + mi * 32 + crow(i, h);
;           const float* src = xrow(p, w, l, b * TPB + ii);
;           float* dstp = isctx ? w.xc1 + (size_t)(b * CTXL + ii) * DM : p.out + (size_t)(b * 8192 + ii - CTXL) * DM;
;           dstp[col] = src[col] + gt * acc[mi][ni][i];
.LBB0_1147:
	v_ashrrev_i32_e32 v49, 31, v48
	v_lshlrev_b64 v[48:49], 13, v[48:49]
	v_lshl_add_u64 v[48:49], v[88:89], 0, v[48:49]
	v_lshl_add_u64 v[48:49], v[48:49], 0, v[66:67]
	v_add_u32_e32 v48, s39, v62
	v_ashrrev_i32_e32 v49, 31, v48
	v_lshlrev_b64 v[48:49], 13, v[48:49]
	v_or_b32_e32 v126, 32, v64
	v_lshl_add_u64 v[48:49], s[4:5], 0, v[48:49]
	v_ashrrev_i32_e32 v127, 31, v126
	v_lshl_add_u64 v[88:89], v[48:49], 0, v[66:67]
	v_lshl_add_u64 v[48:49], v[126:127], 2, s[6:7]
	s_and_b64 vcc, exec, s[40:41]
	s_mov_b64 s[6:7], -1
	s_waitcnt vmcnt(31)
	v_fma_f32 v91, v63, v90, v209
	global_store_dword v[88:89], v91, off
	s_waitcnt vmcnt(32)
	v_add_u32_e32 v171, 0x40000, v170
	global_load_dword v194, v171, s[100:101]
	v_add_u32_e32 v171, 0x42000, v170
	global_load_dword v195, v171, s[100:101]
	v_add_u32_e32 v171, 0x44000, v170
	global_load_dword v196, v171, s[100:101]
	v_add_u32_e32 v171, 0x46000, v170
	global_load_dword v197, v171, s[100:101]
	v_add_u32_e32 v171, 0x50000, v170
	global_load_dword v198, v171, s[100:101]
	v_add_u32_e32 v171, 0x52000, v170
	global_load_dword v199, v171, s[100:101]
	v_add_u32_e32 v171, 0x54000, v170
	global_load_dword v200, v171, s[100:101]
	v_add_u32_e32 v171, 0x56000, v170
	global_load_dword v201, v171, s[100:101]
	v_add_u32_e32 v171, 0x60000, v170
	global_load_dword v202, v171, s[100:101]
	v_add_u32_e32 v171, 0x62000, v170
	global_load_dword v203, v171, s[100:101]
	v_add_u32_e32 v171, 0x64000, v170
	global_load_dword v204, v171, s[100:101]
	v_add_u32_e32 v171, 0x66000, v170
	global_load_dword v205, v171, s[100:101]
	v_add_u32_e32 v171, 0x70000, v170
	global_load_dword v206, v171, s[100:101]
	v_add_u32_e32 v171, 0x72000, v170
	global_load_dword v207, v171, s[100:101]
	v_add_u32_e32 v171, 0x74000, v170
	global_load_dword v208, v171, s[100:101]
	v_add_u32_e32 v171, 0x76000, v170
	global_load_dword v209, v171, s[100:101]
	global_load_dword v125, v[48:49], off
	s_cbranch_vccnz .LBB0_1153
	s_and_saveexec_b64 s[6:7], s[42:43]
	s_xor_b64 s[6:7], exec, s[6:7]
	v_lshlrev_b32_e32 v62, 13, v93
	s_movk_i32 s10, 0xff00
	v_add3_u32 v62, v62, v94, s10
	s_or_saveexec_b64 s[6:7], s[6:7]
	v_mov_b64_e32 v[90:91], s[76:77]
	s_xor_b64 exec, exec, s[6:7]
	v_lshl_add_u32 v62, v93, 8, v94
	v_mov_b64_e32 v[90:91], s[12:13]
	s_or_b64 exec, exec, s[6:7]
	s_mov_b64 s[6:7], 0

; DI int crow(int i, int h) { return (i & 3) + 8 * (i >> 2) + 4 * h; }
; DI const float* xrow(CP p, const Ptrs& w, int l, int tok) {
;   int b = tok / TPB, i = tok - b * TPB;
;   if (l == 0) return i < CTXL ? p.in[2] + (size_t)(b * CTXL + i) * DM : p.in[0] + (size_t)(b * 8192 + i - CTXL) * DM;
;   return i < CTXL ? w.xc1 + (size_t)(b * CTXL + i) * DM : p.out + (size_t)(b * 8192 + i - CTXL) * DM;
; DI void phase_out(CP p, const Ptrs& w, int l, bf16_t* sA, bf16_t* sB) {
;     ...
;         int col = n0 + wn * 64 + ni * 32 + r;
;         float gt = gate[col];
; #pragma unroll
;         for (int i = 0; i < 16; ++i) {
;           int ii = ib + wm * 64 + mi * 32 + crow(i, h);
;           const float* src = xrow(p, w, l, b * TPB + ii);
;           float* dstp = isctx ? w.xc1 + (size_t)(b * CTXL + ii) * DM : p.out + (size_t)(b * 8192 + ii - CTXL) * DM;
;           dstp[col] = src[col] + gt * acc[mi][ni][i];
.LBB0_1159:
	v_ashrrev_i32_e32 v63, 31, v62
	v_lshlrev_b64 v[62:63], 13, v[62:63]
	v_lshl_add_u64 v[62:63], v[90:91], 0, v[62:63]
	v_lshl_add_u64 v[62:63], v[64:65], 2, v[62:63]
	s_and_b64 vcc, exec, s[40:41]
	s_mov_b64 s[6:7], -1
	s_waitcnt vmcnt(0)
	v_fma_f32 v62, v32, v125, v210
	global_store_dword v[70:71], v62, off offset:128
	s_cbranch_vccnz .LBB0_1165
	s_and_saveexec_b64 s[6:7], s[44:45]
	s_xor_b64 s[6:7], exec, s[6:7]
	v_lshlrev_b32_e32 v32, 13, v95
	s_movk_i32 s10, 0xff00
	v_add3_u32 v62, v32, v96, s10
	s_or_saveexec_b64 s[6:7], s[6:7]
	v_mov_b64_e32 v[70:71], s[76:77]
	s_xor_b64 exec, exec, s[6:7]
	v_lshl_add_u32 v62, v95, 8, v96
	v_mov_b64_e32 v[70:71], s[12:13]
	s_or_b64 exec, exec, s[6:7]
	s_mov_b64 s[6:7], 0

; DI int crow(int i, int h) { return (i & 3) + 8 * (i >> 2) + 4 * h; }
; DI const float* xrow(CP p, const Ptrs& w, int l, int tok) {
;   int b = tok / TPB, i = tok - b * TPB;
;   if (l == 0) return i < CTXL ? p.in[2] + (size_t)(b * CTXL + i) * DM : p.in[0] + (size_t)(b * 8192 + i - CTXL) * DM;
;   return i < CTXL ? w.xc1 + (size_t)(b * CTXL + i) * DM : p.out + (size_t)(b * 8192 + i - CTXL) * DM;
; DI void phase_out(CP p, const Ptrs& w, int l, bf16_t* sA, bf16_t* sB) {
;     ...
;         int col = n0 + wn * 64 + ni * 32 + r;
;         float gt = gate[col];
; #pragma unroll
;         for (int i = 0; i < 16; ++i) {
;           int ii = ib + wm * 64 + mi * 32 + crow(i, h);
;           const float* src = xrow(p, w, l, b * TPB + ii);
;           float* dstp = isctx ? w.xc1 + (size_t)(b * CTXL + ii) * DM : p.out + (size_t)(b * 8192 + ii - CTXL) * DM;
;           dstp[col] = src[col] + gt * acc[mi][ni][i];
.LBB0_1171:
	v_ashrrev_i32_e32 v63, 31, v62
	v_lshlrev_b64 v[62:63], 13, v[62:63]
	v_lshl_add_u64 v[62:63], v[70:71], 0, v[62:63]
	v_lshl_add_u64 v[62:63], v[64:65], 2, v[62:63]
	s_and_b64 vcc, exec, s[40:41]
	s_mov_b64 s[6:7], -1
	s_waitcnt vmcnt(1)
	v_fma_f32 v32, v33, v125, v211
	global_store_dword v[72:73], v32, off offset:128
	s_cbranch_vccnz .LBB0_1177
	s_and_saveexec_b64 s[6:7], s[46:47]
	s_xor_b64 s[6:7], exec, s[6:7]
	v_lshlrev_b32_e32 v32, 13, v97
	s_movk_i32 s10, 0xff00
	v_add3_u32 v32, v32, v98, s10
	s_or_saveexec_b64 s[6:7], s[6:7]
	v_mov_b64_e32 v[62:63], s[76:77]
	s_xor_b64 exec, exec, s[6:7]
	v_lshl_add_u32 v32, v97, 8, v98
	v_mov_b64_e32 v[62:63], s[12:13]
	s_or_b64 exec, exec, s[6:7]
	s_mov_b64 s[6:7], 0

; DI int crow(int i, int h) { return (i & 3) + 8 * (i >> 2) + 4 * h; }
; DI const float* xrow(CP p, const Ptrs& w, int l, int tok) {
;   int b = tok / TPB, i = tok - b * TPB;
;   if (l == 0) return i < CTXL ? p.in[2] + (size_t)(b * CTXL + i) * DM : p.in[0] + (size_t)(b * 8192 + i - CTXL) * DM;
;   return i < CTXL ? w.xc1 + (size_t)(b * CTXL + i) * DM : p.out + (size_t)(b * 8192 + i - CTXL) * DM;
; DI void phase_out(CP p, const Ptrs& w, int l, bf16_t* sA, bf16_t* sB) {
;     ...
;         int col = n0 + wn * 64 + ni * 32 + r;
;         float gt = gate[col];
; #pragma unroll
;         for (int i = 0; i < 16; ++i) {
;           int ii = ib + wm * 64 + mi * 32 + crow(i, h);
;           const float* src = xrow(p, w, l, b * TPB + ii);
;           float* dstp = isctx ? w.xc1 + (size_t)(b * CTXL + ii) * DM : p.out + (size_t)(b * 8192 + ii - CTXL) * DM;
;           dstp[col] = src[col] + gt * acc[mi][ni][i];
.LBB0_1183:
	v_ashrrev_i32_e32 v33, 31, v32
	v_lshlrev_b64 v[32:33], 13, v[32:33]
	v_lshl_add_u64 v[32:33], v[62:63], 0, v[32:33]
	v_lshl_add_u64 v[32:33], v[64:65], 2, v[32:33]
	s_and_b64 vcc, exec, s[40:41]
	s_mov_b64 s[6:7], -1
	s_waitcnt vmcnt(2)
	v_fma_f32 v32, v34, v125, v212
	global_store_dword v[74:75], v32, off offset:128
	s_cbranch_vccnz .LBB0_1189
	s_and_saveexec_b64 s[6:7], s[48:49]
	s_xor_b64 s[6:7], exec, s[6:7]
	v_lshlrev_b32_e32 v32, 13, v99
	s_movk_i32 s10, 0xff00
	v_add3_u32 v32, v32, v100, s10
	s_or_saveexec_b64 s[6:7], s[6:7]
	v_mov_b64_e32 v[62:63], s[76:77]
	s_xor_b64 exec, exec, s[6:7]
	v_lshl_add_u32 v32, v99, 8, v100
	v_mov_b64_e32 v[62:63], s[12:13]
	s_or_b64 exec, exec, s[6:7]
	s_mov_b64 s[6:7], 0

; DI int crow(int i, int h) { return (i & 3) + 8 * (i >> 2) + 4 * h; }
; DI const float* xrow(CP p, const Ptrs& w, int l, int tok) {
;   int b = tok / TPB, i = tok - b * TPB;
;   if (l == 0) return i < CTXL ? p.in[2] + (size_t)(b * CTXL + i) * DM : p.in[0] + (size_t)(b * 8192 + i - CTXL) * DM;
;   return i < CTXL ? w.xc1 + (size_t)(b * CTXL + i) * DM : p.out + (size_t)(b * 8192 + i - CTXL) * DM;
; DI void phase_out(CP p, const Ptrs& w, int l, bf16_t* sA, bf16_t* sB) {
;     ...
;         int col = n0 + wn * 64 + ni * 32 + r;
;         float gt = gate[col];
; #pragma unroll
;         for (int i = 0; i < 16; ++i) {
;           int ii = ib + wm * 64 + mi * 32 + crow(i, h);
;           const float* src = xrow(p, w, l, b * TPB + ii);
;           float* dstp = isctx ? w.xc1 + (size_t)(b * CTXL + ii) * DM : p.out + (size_t)(b * 8192 + ii - CTXL) * DM;
;           dstp[col] = src[col] + gt * acc[mi][ni][i];
.LBB0_1195:
	v_ashrrev_i32_e32 v33, 31, v32
	v_lshlrev_b64 v[32:33], 13, v[32:33]
	v_lshl_add_u64 v[32:33], v[62:63], 0, v[32:33]
	v_lshl_add_u64 v[32:33], v[64:65], 2, v[32:33]
	s_and_b64 vcc, exec, s[40:41]
	s_mov_b64 s[6:7], -1
	s_waitcnt vmcnt(3)
	v_fma_f32 v32, v35, v125, v213
	global_store_dword v[50:51], v32, off offset:128
	s_cbranch_vccnz .LBB0_1201
	s_and_saveexec_b64 s[6:7], s[50:51]
	s_xor_b64 s[6:7], exec, s[6:7]
	v_lshlrev_b32_e32 v32, 13, v101
	s_movk_i32 s10, 0xff00
	v_add3_u32 v32, v32, v102, s10
	s_or_saveexec_b64 s[6:7], s[6:7]
	v_mov_b64_e32 v[34:35], s[76:77]
	s_xor_b64 exec, exec, s[6:7]
	v_lshl_add_u32 v32, v101, 8, v102
	v_mov_b64_e32 v[34:35], s[12:13]
	s_or_b64 exec, exec, s[6:7]
	s_mov_b64 s[6:7], 0

; DI int crow(int i, int h) { return (i & 3) + 8 * (i >> 2) + 4 * h; }
; DI const float* xrow(CP p, const Ptrs& w, int l, int tok) {
;   int b = tok / TPB, i = tok - b * TPB;
;   if (l == 0) return i < CTXL ? p.in[2] + (size_t)(b * CTXL + i) * DM : p.in[0] + (size_t)(b * 8192 + i - CTXL) * DM;
;   return i < CTXL ? w.xc1 + (size_t)(b * CTXL + i) * DM : p.out + (size_t)(b * 8192 + i - CTXL) * DM;
; DI void phase_out(CP p, const Ptrs& w, int l, bf16_t* sA, bf16_t* sB) {
;     ...
;         int col = n0 + wn * 64 + ni * 32 + r;
;         float gt = gate[col];
; #pragma unroll
;         for (int i = 0; i < 16; ++i) {
;           int ii = ib + wm * 64 + mi * 32 + crow(i, h);
;           const float* src = xrow(p, w, l, b * TPB + ii);
;           float* dstp = isctx ? w.xc1 + (size_t)(b * CTXL + ii) * DM : p.out + (size_t)(b * 8192 + ii - CTXL) * DM;
;           dstp[col] = src[col] + gt * acc[mi][ni][i];
.LBB0_1207:
	v_ashrrev_i32_e32 v33, 31, v32
	v_lshlrev_b64 v[32:33], 13, v[32:33]
	v_lshl_add_u64 v[32:33], v[34:35], 0, v[32:33]
	v_lshl_add_u64 v[32:33], v[64:65], 2, v[32:33]
	s_and_b64 vcc, exec, s[40:41]
	s_mov_b64 s[6:7], -1
	s_waitcnt vmcnt(4)
	v_fma_f32 v32, v36, v125, v172
	global_store_dword v[76:77], v32, off offset:128
	s_cbranch_vccnz .LBB0_1213
	s_and_saveexec_b64 s[6:7], s[52:53]
	s_xor_b64 s[6:7], exec, s[6:7]
	v_lshlrev_b32_e32 v32, 13, v103
	s_movk_i32 s10, 0xff00
	v_add3_u32 v32, v32, v104, s10
	s_or_saveexec_b64 s[6:7], s[6:7]
	v_mov_b64_e32 v[34:35], s[76:77]
	s_xor_b64 exec, exec, s[6:7]
	v_lshl_add_u32 v32, v103, 8, v104
	v_mov_b64_e32 v[34:35], s[12:13]
	s_or_b64 exec, exec, s[6:7]
	s_mov_b64 s[6:7], 0

; DI int crow(int i, int h) { return (i & 3) + 8 * (i >> 2) + 4 * h; }
; DI const float* xrow(CP p, const Ptrs& w, int l, int tok) {
;   int b = tok / TPB, i = tok - b * TPB;
;   if (l == 0) return i < CTXL ? p.in[2] + (size_t)(b * CTXL + i) * DM : p.in[0] + (size_t)(b * 8192 + i - CTXL) * DM;
;   return i < CTXL ? w.xc1 + (size_t)(b * CTXL + i) * DM : p.out + (size_t)(b * 8192 + i - CTXL) * DM;
; DI void phase_out(CP p, const Ptrs& w, int l, bf16_t* sA, bf16_t* sB) {
;     ...
;         int col = n0 + wn * 64 + ni * 32 + r;
;         float gt = gate[col];
; #pragma unroll
;         for (int i = 0; i < 16; ++i) {
;           int ii = ib + wm * 64 + mi * 32 + crow(i, h);
;           const float* src = xrow(p, w, l, b * TPB + ii);
;           float* dstp = isctx ? w.xc1 + (size_t)(b * CTXL + ii) * DM : p.out + (size_t)(b * 8192 + ii - CTXL) * DM;
;           dstp[col] = src[col] + gt * acc[mi][ni][i];
.LBB0_1219:
	v_ashrrev_i32_e32 v33, 31, v32
	v_lshlrev_b64 v[32:33], 13, v[32:33]
	v_lshl_add_u64 v[32:33], v[34:35], 0, v[32:33]
	v_lshl_add_u64 v[32:33], v[64:65], 2, v[32:33]
	s_and_b64 vcc, exec, s[40:41]
	s_mov_b64 s[6:7], -1
	s_waitcnt vmcnt(5)
	v_fma_f32 v32, v37, v125, v173
	global_store_dword v[52:53], v32, off offset:128
	s_cbranch_vccnz .LBB0_1225
	s_and_saveexec_b64 s[6:7], s[54:55]
	s_xor_b64 s[6:7], exec, s[6:7]
	v_lshlrev_b32_e32 v32, 13, v105
	s_movk_i32 s10, 0xff00
	v_add3_u32 v32, v32, v106, s10
	s_or_saveexec_b64 s[6:7], s[6:7]
	v_mov_b64_e32 v[34:35], s[76:77]
	s_xor_b64 exec, exec, s[6:7]
	v_lshl_add_u32 v32, v105, 8, v106
	v_mov_b64_e32 v[34:35], s[12:13]
	s_or_b64 exec, exec, s[6:7]
	s_mov_b64 s[6:7], 0

; DI int crow(int i, int h) { return (i & 3) + 8 * (i >> 2) + 4 * h; }
; DI const float* xrow(CP p, const Ptrs& w, int l, int tok) {
;   int b = tok / TPB, i = tok - b * TPB;
;   if (l == 0) return i < CTXL ? p.in[2] + (size_t)(b * CTXL + i) * DM : p.in[0] + (size_t)(b * 8192 + i - CTXL) * DM;
;   return i < CTXL ? w.xc1 + (size_t)(b * CTXL + i) * DM : p.out + (size_t)(b * 8192 + i - CTXL) * DM;
; DI void phase_out(CP p, const Ptrs& w, int l, bf16_t* sA, bf16_t* sB) {
;     ...
;         int col = n0 + wn * 64 + ni * 32 + r;
;         float gt = gate[col];
; #pragma unroll
;         for (int i = 0; i < 16; ++i) {
;           int ii = ib + wm * 64 + mi * 32 + crow(i, h);
;           const float* src = xrow(p, w, l, b * TPB + ii);
;           float* dstp = isctx ? w.xc1 + (size_t)(b * CTXL + ii) * DM : p.out + (size_t)(b * 8192 + ii - CTXL) * DM;
;           dstp[col] = src[col] + gt * acc[mi][ni][i];
.LBB0_1231:
	v_ashrrev_i32_e32 v33, 31, v32
	v_lshlrev_b64 v[32:33], 13, v[32:33]
	v_lshl_add_u64 v[32:33], v[34:35], 0, v[32:33]
	v_lshl_add_u64 v[32:33], v[64:65], 2, v[32:33]
	s_and_b64 vcc, exec, s[40:41]
	s_mov_b64 s[6:7], -1
	s_waitcnt vmcnt(6)
	v_fma_f32 v32, v38, v125, v174
	global_store_dword v[78:79], v32, off offset:128
	s_cbranch_vccnz .LBB0_1237
	s_and_saveexec_b64 s[6:7], s[56:57]
	s_xor_b64 s[6:7], exec, s[6:7]
	v_lshlrev_b32_e32 v32, 13, v107
	s_movk_i32 s10, 0xff00
	v_add3_u32 v32, v32, v108, s10
	s_or_saveexec_b64 s[6:7], s[6:7]
	v_mov_b64_e32 v[34:35], s[76:77]
	s_xor_b64 exec, exec, s[6:7]
	v_lshl_add_u32 v32, v107, 8, v108
	v_mov_b64_e32 v[34:35], s[12:13]
	s_or_b64 exec, exec, s[6:7]
	s_mov_b64 s[6:7], 0

; DI int crow(int i, int h) { return (i & 3) + 8 * (i >> 2) + 4 * h; }
; DI const float* xrow(CP p, const Ptrs& w, int l, int tok) {
;   int b = tok / TPB, i = tok - b * TPB;
;   if (l == 0) return i < CTXL ? p.in[2] + (size_t)(b * CTXL + i) * DM : p.in[0] + (size_t)(b * 8192 + i - CTXL) * DM;
;   return i < CTXL ? w.xc1 + (size_t)(b * CTXL + i) * DM : p.out + (size_t)(b * 8192 + i - CTXL) * DM;
; DI void phase_out(CP p, const Ptrs& w, int l, bf16_t* sA, bf16_t* sB) {
;     ...
;         int col = n0 + wn * 64 + ni * 32 + r;
;         float gt = gate[col];
; #pragma unroll
;         for (int i = 0; i < 16; ++i) {
;           int ii = ib + wm * 64 + mi * 32 + crow(i, h);
;           const float* src = xrow(p, w, l, b * TPB + ii);
;           float* dstp = isctx ? w.xc1 + (size_t)(b * CTXL + ii) * DM : p.out + (size_t)(b * 8192 + ii - CTXL) * DM;
;           dstp[col] = src[col] + gt * acc[mi][ni][i];
.LBB0_1243:
	v_ashrrev_i32_e32 v33, 31, v32
	v_lshlrev_b64 v[32:33], 13, v[32:33]
	v_lshl_add_u64 v[32:33], v[34:35], 0, v[32:33]
	v_lshl_add_u64 v[32:33], v[64:65], 2, v[32:33]
	s_and_b64 vcc, exec, s[40:41]
	s_mov_b64 s[6:7], -1
	s_waitcnt vmcnt(7)
	v_fma_f32 v32, v39, v125, v175
	global_store_dword v[54:55], v32, off offset:128
	s_cbranch_vccnz .LBB0_1249
	s_and_saveexec_b64 s[6:7], s[58:59]
	s_xor_b64 s[6:7], exec, s[6:7]
	v_lshlrev_b32_e32 v32, 13, v109
	s_movk_i32 s10, 0xff00
	v_add3_u32 v32, v32, v110, s10
	s_or_saveexec_b64 s[6:7], s[6:7]
	v_mov_b64_e32 v[34:35], s[76:77]
	s_xor_b64 exec, exec, s[6:7]
	v_lshl_add_u32 v32, v109, 8, v110
	v_mov_b64_e32 v[34:35], s[12:13]
	s_or_b64 exec, exec, s[6:7]
	s_mov_b64 s[6:7], 0

; DI int crow(int i, int h) { return (i & 3) + 8 * (i >> 2) + 4 * h; }
; DI const float* xrow(CP p, const Ptrs& w, int l, int tok) {
;   int b = tok / TPB, i = tok - b * TPB;
;   if (l == 0) return i < CTXL ? p.in[2] + (size_t)(b * CTXL + i) * DM : p.in[0] + (size_t)(b * 8192 + i - CTXL) * DM;
;   return i < CTXL ? w.xc1 + (size_t)(b * CTXL + i) * DM : p.out + (size_t)(b * 8192 + i - CTXL) * DM;
; DI void phase_out(CP p, const Ptrs& w, int l, bf16_t* sA, bf16_t* sB) {
;     ...
;         int col = n0 + wn * 64 + ni * 32 + r;
;         float gt = gate[col];
; #pragma unroll
;         for (int i = 0; i < 16; ++i) {
;           int ii = ib + wm * 64 + mi * 32 + crow(i, h);
;           const float* src = xrow(p, w, l, b * TPB + ii);
;           float* dstp = isctx ? w.xc1 + (size_t)(b * CTXL + ii) * DM : p.out + (size_t)(b * 8192 + ii - CTXL) * DM;
;           dstp[col] = src[col] + gt * acc[mi][ni][i];
.LBB0_1255:
	v_ashrrev_i32_e32 v33, 31, v32
	v_lshlrev_b64 v[32:33], 13, v[32:33]
	v_lshl_add_u64 v[32:33], v[34:35], 0, v[32:33]
	v_lshl_add_u64 v[32:33], v[64:65], 2, v[32:33]
	s_and_b64 vcc, exec, s[40:41]
	s_mov_b64 s[6:7], -1
	s_waitcnt vmcnt(8)
	v_fma_f32 v32, v40, v125, v176
	global_store_dword v[80:81], v32, off offset:128
	s_cbranch_vccnz .LBB0_1261
	s_and_saveexec_b64 s[6:7], s[60:61]
	s_xor_b64 s[6:7], exec, s[6:7]
	v_lshlrev_b32_e32 v32, 13, v111
	s_movk_i32 s10, 0xff00
	v_add3_u32 v32, v32, v112, s10
	s_or_saveexec_b64 s[6:7], s[6:7]
	v_mov_b64_e32 v[34:35], s[76:77]
	s_xor_b64 exec, exec, s[6:7]
	v_lshl_add_u32 v32, v111, 8, v112
	v_mov_b64_e32 v[34:35], s[12:13]
	s_or_b64 exec, exec, s[6:7]
	s_mov_b64 s[6:7], 0

; DI int crow(int i, int h) { return (i & 3) + 8 * (i >> 2) + 4 * h; }
; DI const float* xrow(CP p, const Ptrs& w, int l, int tok) {
;   int b = tok / TPB, i = tok - b * TPB;
;   if (l == 0) return i < CTXL ? p.in[2] + (size_t)(b * CTXL + i) * DM : p.in[0] + (size_t)(b * 8192 + i - CTXL) * DM;
;   return i < CTXL ? w.xc1 + (size_t)(b * CTXL + i) * DM : p.out + (size_t)(b * 8192 + i - CTXL) * DM;
; DI void phase_out(CP p, const Ptrs& w, int l, bf16_t* sA, bf16_t* sB) {
;     ...
;         int col = n0 + wn * 64 + ni * 32 + r;
;         float gt = gate[col];
; #pragma unroll
;         for (int i = 0; i < 16; ++i) {
;           int ii = ib + wm * 64 + mi * 32 + crow(i, h);
;           const float* src = xrow(p, w, l, b * TPB + ii);
;           float* dstp = isctx ? w.xc1 + (size_t)(b * CTXL + ii) * DM : p.out + (size_t)(b * 8192 + ii - CTXL) * DM;
;           dstp[col] = src[col] + gt * acc[mi][ni][i];
.LBB0_1267:
	v_ashrrev_i32_e32 v33, 31, v32
	v_lshlrev_b64 v[32:33], 13, v[32:33]
	v_lshl_add_u64 v[32:33], v[34:35], 0, v[32:33]
	v_lshl_add_u64 v[32:33], v[64:65], 2, v[32:33]
	s_and_b64 vcc, exec, s[40:41]
	s_mov_b64 s[6:7], -1
	s_waitcnt vmcnt(9)
	v_fma_f32 v32, v41, v125, v177
	global_store_dword v[56:57], v32, off offset:128
	s_cbranch_vccnz .LBB0_1273
	s_and_saveexec_b64 s[6:7], s[62:63]
	s_xor_b64 s[6:7], exec, s[6:7]
	v_lshlrev_b32_e32 v32, 13, v113
	s_movk_i32 s10, 0xff00
	v_add3_u32 v32, v32, v114, s10
	s_or_saveexec_b64 s[6:7], s[6:7]
	v_mov_b64_e32 v[34:35], s[76:77]
	s_xor_b64 exec, exec, s[6:7]
	v_lshl_add_u32 v32, v113, 8, v114
	v_mov_b64_e32 v[34:35], s[12:13]
	s_or_b64 exec, exec, s[6:7]
	s_mov_b64 s[6:7], 0

; DI int crow(int i, int h) { return (i & 3) + 8 * (i >> 2) + 4 * h; }
; DI const float* xrow(CP p, const Ptrs& w, int l, int tok) {
;   int b = tok / TPB, i = tok - b * TPB;
;   if (l == 0) return i < CTXL ? p.in[2] + (size_t)(b * CTXL + i) * DM : p.in[0] + (size_t)(b * 8192 + i - CTXL) * DM;
;   return i < CTXL ? w.xc1 + (size_t)(b * CTXL + i) * DM : p.out + (size_t)(b * 8192 + i - CTXL) * DM;
; DI void phase_out(CP p, const Ptrs& w, int l, bf16_t* sA, bf16_t* sB) {
;     ...
;         int col = n0 + wn * 64 + ni * 32 + r;
;         float gt = gate[col];
; #pragma unroll
;         for (int i = 0; i < 16; ++i) {
;           int ii = ib + wm * 64 + mi * 32 + crow(i, h);
;           const float* src = xrow(p, w, l, b * TPB + ii);
;           float* dstp = isctx ? w.xc1 + (size_t)(b * CTXL + ii) * DM : p.out + (size_t)(b * 8192 + ii - CTXL) * DM;
;           dstp[col] = src[col] + gt * acc[mi][ni][i];
.LBB0_1279:
	v_ashrrev_i32_e32 v33, 31, v32
	v_lshlrev_b64 v[32:33], 13, v[32:33]
	v_lshl_add_u64 v[32:33], v[34:35], 0, v[32:33]
	v_lshl_add_u64 v[32:33], v[64:65], 2, v[32:33]
	s_and_b64 vcc, exec, s[40:41]
	s_mov_b64 s[6:7], -1
	s_waitcnt vmcnt(10)
	v_fma_f32 v32, v42, v125, v178
	global_store_dword v[82:83], v32, off offset:128
	s_cbranch_vccnz .LBB0_1285
	s_and_saveexec_b64 s[6:7], s[64:65]
	s_xor_b64 s[6:7], exec, s[6:7]
	v_lshlrev_b32_e32 v32, 13, v115
	s_movk_i32 s10, 0xff00
	v_add3_u32 v32, v32, v116, s10
	s_or_saveexec_b64 s[6:7], s[6:7]
	v_mov_b64_e32 v[34:35], s[76:77]
	s_xor_b64 exec, exec, s[6:7]
	v_lshl_add_u32 v32, v115, 8, v116
	v_mov_b64_e32 v[34:35], s[12:13]
	s_or_b64 exec, exec, s[6:7]
	s_mov_b64 s[6:7], 0

; DI int crow(int i, int h) { return (i & 3) + 8 * (i >> 2) + 4 * h; }
; DI const float* xrow(CP p, const Ptrs& w, int l, int tok) {
;   int b = tok / TPB, i = tok - b * TPB;
;   if (l == 0) return i < CTXL ? p.in[2] + (size_t)(b * CTXL + i) * DM : p.in[0] + (size_t)(b * 8192 + i - CTXL) * DM;
;   return i < CTXL ? w.xc1 + (size_t)(b * CTXL + i) * DM : p.out + (size_t)(b * 8192 + i - CTXL) * DM;
; DI void phase_out(CP p, const Ptrs& w, int l, bf16_t* sA, bf16_t* sB) {
;     ...
;         int col = n0 + wn * 64 + ni * 32 + r;
;         float gt = gate[col];
; #pragma unroll
;         for (int i = 0; i < 16; ++i) {
;           int ii = ib + wm * 64 + mi * 32 + crow(i, h);
;           const float* src = xrow(p, w, l, b * TPB + ii);
;           float* dstp = isctx ? w.xc1 + (size_t)(b * CTXL + ii) * DM : p.out + (size_t)(b * 8192 + ii - CTXL) * DM;
;           dstp[col] = src[col] + gt * acc[mi][ni][i];
.LBB0_1291:
	v_ashrrev_i32_e32 v33, 31, v32
	v_lshlrev_b64 v[32:33], 13, v[32:33]
	v_lshl_add_u64 v[32:33], v[34:35], 0, v[32:33]
	v_lshl_add_u64 v[32:33], v[64:65], 2, v[32:33]
	s_and_b64 vcc, exec, s[40:41]
	s_mov_b64 s[6:7], -1
	s_waitcnt vmcnt(11)
	v_fma_f32 v32, v43, v125, v179
	global_store_dword v[58:59], v32, off offset:128
	s_cbranch_vccnz .LBB0_1297
	s_and_saveexec_b64 s[6:7], s[66:67]
	s_xor_b64 s[6:7], exec, s[6:7]
	v_lshlrev_b32_e32 v32, 13, v117
	s_movk_i32 s10, 0xff00
	v_add3_u32 v32, v32, v118, s10
	s_or_saveexec_b64 s[6:7], s[6:7]
	v_mov_b64_e32 v[34:35], s[76:77]
	s_xor_b64 exec, exec, s[6:7]
	v_lshl_add_u32 v32, v117, 8, v118
	v_mov_b64_e32 v[34:35], s[12:13]
	s_or_b64 exec, exec, s[6:7]
	s_mov_b64 s[6:7], 0

; DI int crow(int i, int h) { return (i & 3) + 8 * (i >> 2) + 4 * h; }
; DI const float* xrow(CP p, const Ptrs& w, int l, int tok) {
;   int b = tok / TPB, i = tok - b * TPB;
;   if (l == 0) return i < CTXL ? p.in[2] + (size_t)(b * CTXL + i) * DM : p.in[0] + (size_t)(b * 8192 + i - CTXL) * DM;
;   return i < CTXL ? w.xc1 + (size_t)(b * CTXL + i) * DM : p.out + (size_t)(b * 8192 + i - CTXL) * DM;
; DI void phase_out(CP p, const Ptrs& w, int l, bf16_t* sA, bf16_t* sB) {
;     ...
;         int col = n0 + wn * 64 + ni * 32 + r;
;         float gt = gate[col];
; #pragma unroll
;         for (int i = 0; i < 16; ++i) {
;           int ii = ib + wm * 64 + mi * 32 + crow(i, h);
;           const float* src = xrow(p, w, l, b * TPB + ii);
;           float* dstp = isctx ? w.xc1 + (size_t)(b * CTXL + ii) * DM : p.out + (size_t)(b * 8192 + ii - CTXL) * DM;
;           dstp[col] = src[col] + gt * acc[mi][ni][i];
.LBB0_1303:
	v_ashrrev_i32_e32 v33, 31, v32
	v_lshlrev_b64 v[32:33], 13, v[32:33]
	v_lshl_add_u64 v[32:33], v[34:35], 0, v[32:33]
	v_lshl_add_u64 v[32:33], v[64:65], 2, v[32:33]
	s_and_b64 vcc, exec, s[40:41]
	s_mov_b64 s[6:7], -1
	s_waitcnt vmcnt(12)
	v_fma_f32 v32, v44, v125, v132
	global_store_dword v[84:85], v32, off offset:128
	s_cbranch_vccnz .LBB0_1309
	s_and_saveexec_b64 s[6:7], s[68:69]
	s_xor_b64 s[6:7], exec, s[6:7]
	v_lshlrev_b32_e32 v32, 13, v119
	s_movk_i32 s10, 0xff00
	v_add3_u32 v32, v32, v120, s10
	s_or_saveexec_b64 s[6:7], s[6:7]
	v_mov_b64_e32 v[34:35], s[76:77]
	s_xor_b64 exec, exec, s[6:7]
	v_lshl_add_u32 v32, v119, 8, v120
	v_mov_b64_e32 v[34:35], s[12:13]
	s_or_b64 exec, exec, s[6:7]
	s_mov_b64 s[6:7], 0

; DI int crow(int i, int h) { return (i & 3) + 8 * (i >> 2) + 4 * h; }
; DI const float* xrow(CP p, const Ptrs& w, int l, int tok) {
;   int b = tok / TPB, i = tok - b * TPB;
;   if (l == 0) return i < CTXL ? p.in[2] + (size_t)(b * CTXL + i) * DM : p.in[0] + (size_t)(b * 8192 + i - CTXL) * DM;
;   return i < CTXL ? w.xc1 + (size_t)(b * CTXL + i) * DM : p.out + (size_t)(b * 8192 + i - CTXL) * DM;
; DI void phase_out(CP p, const Ptrs& w, int l, bf16_t* sA, bf16_t* sB) {
;     ...
;         int col = n0 + wn * 64 + ni * 32 + r;
;         float gt = gate[col];
; #pragma unroll
;         for (int i = 0; i < 16; ++i) {
;           int ii = ib + wm * 64 + mi * 32 + crow(i, h);
;           const float* src = xrow(p, w, l, b * TPB + ii);
;           float* dstp = isctx ? w.xc1 + (size_t)(b * CTXL + ii) * DM : p.out + (size_t)(b * 8192 + ii - CTXL) * DM;
;           dstp[col] = src[col] + gt * acc[mi][ni][i];
.LBB0_1315:
	v_ashrrev_i32_e32 v33, 31, v32
	v_lshlrev_b64 v[32:33], 13, v[32:33]
	v_lshl_add_u64 v[32:33], v[34:35], 0, v[32:33]
	v_lshl_add_u64 v[32:33], v[64:65], 2, v[32:33]
	s_and_b64 vcc, exec, s[40:41]
	s_mov_b64 s[6:7], -1
	s_waitcnt vmcnt(13)
	v_fma_f32 v32, v45, v125, v133
	global_store_dword v[60:61], v32, off offset:128
	s_cbranch_vccnz .LBB0_1321
	s_and_saveexec_b64 s[6:7], s[70:71]
	s_xor_b64 s[6:7], exec, s[6:7]
	v_lshlrev_b32_e32 v32, 13, v121
	s_movk_i32 s10, 0xff00
	v_add3_u32 v32, v32, v122, s10
	s_or_saveexec_b64 s[6:7], s[6:7]
	v_mov_b64_e32 v[34:35], s[76:77]
	s_xor_b64 exec, exec, s[6:7]
	v_lshl_add_u32 v32, v121, 8, v122
	v_mov_b64_e32 v[34:35], s[12:13]
	s_or_b64 exec, exec, s[6:7]
	s_mov_b64 s[6:7], 0

; DI int crow(int i, int h) { return (i & 3) + 8 * (i >> 2) + 4 * h; }
; DI const float* xrow(CP p, const Ptrs& w, int l, int tok) {
;   int b = tok / TPB, i = tok - b * TPB;
;   if (l == 0) return i < CTXL ? p.in[2] + (size_t)(b * CTXL + i) * DM : p.in[0] + (size_t)(b * 8192 + i - CTXL) * DM;
;   return i < CTXL ? w.xc1 + (size_t)(b * CTXL + i) * DM : p.out + (size_t)(b * 8192 + i - CTXL) * DM;
; DI void phase_out(CP p, const Ptrs& w, int l, bf16_t* sA, bf16_t* sB) {
;     ...
;         int col = n0 + wn * 64 + ni * 32 + r;
;         float gt = gate[col];
; #pragma unroll
;         for (int i = 0; i < 16; ++i) {
;           int ii = ib + wm * 64 + mi * 32 + crow(i, h);
;           const float* src = xrow(p, w, l, b * TPB + ii);
;           float* dstp = isctx ? w.xc1 + (size_t)(b * CTXL + ii) * DM : p.out + (size_t)(b * 8192 + ii - CTXL) * DM;
;           dstp[col] = src[col] + gt * acc[mi][ni][i];
.LBB0_1327:
	v_ashrrev_i32_e32 v33, 31, v32
	v_lshlrev_b64 v[32:33], 13, v[32:33]
	v_lshl_add_u64 v[32:33], v[34:35], 0, v[32:33]
	v_lshl_add_u64 v[32:33], v[64:65], 2, v[32:33]
	s_and_b64 vcc, exec, s[40:41]
	s_mov_b64 s[6:7], -1
	s_waitcnt vmcnt(14)
	v_fma_f32 v32, v46, v125, v134
	global_store_dword v[86:87], v32, off offset:128
	s_cbranch_vccnz .LBB0_1333
	s_and_saveexec_b64 s[6:7], s[72:73]
	s_xor_b64 s[6:7], exec, s[6:7]
	v_lshlrev_b32_e32 v32, 13, v123
	s_movk_i32 s10, 0xff00
	v_add3_u32 v32, v32, v124, s10
	s_or_saveexec_b64 s[6:7], s[6:7]
	v_mov_b64_e32 v[34:35], s[76:77]
	s_xor_b64 exec, exec, s[6:7]
	v_lshl_add_u32 v32, v123, 8, v124
	v_mov_b64_e32 v[34:35], s[12:13]
	s_or_b64 exec, exec, s[6:7]
	s_mov_b64 s[6:7], 0

; DI int crow(int i, int h) { return (i & 3) + 8 * (i >> 2) + 4 * h; }
; DI void phase_out(CP p, const Ptrs& w, int l, bf16_t* sA, bf16_t* sB) {
;     ...
;         int col = n0 + wn * 64 + ni * 32 + r;
;         float gt = gate[col];
; #pragma unroll
;         for (int i = 0; i < 16; ++i) {
;           int ii = ib + wm * 64 + mi * 32 + crow(i, h);
;           const float* src = xrow(p, w, l, b * TPB + ii);
;           float* dstp = isctx ? w.xc1 + (size_t)(b * CTXL + ii) * DM : p.out + (size_t)(b * 8192 + ii - CTXL) * DM;
;           dstp[col] = src[col] + gt * acc[mi][ni][i];
.LBB0_1339:
	v_ashrrev_i32_e32 v33, 31, v32
	v_lshlrev_b64 v[32:33], 13, v[32:33]
	v_lshl_add_u64 v[32:33], v[34:35], 0, v[32:33]
	v_lshl_add_u64 v[32:33], v[64:65], 2, v[32:33]
	v_or_b32_e32 v52, 32, v92
	v_or_b32_e32 v36, v52, v164
	s_and_b64 vcc, exec, s[40:41]
	s_mov_b64 s[6:7], -1
	s_waitcnt vmcnt(15)
	v_fma_f32 v32, v47, v125, v135
	global_store_dword v[88:89], v32, off offset:128
	s_waitcnt vmcnt(32)
	v_add_u32_e32 v171, 0x40080, v170
	global_load_dword v210, v171, s[100:101]
	v_add_u32_e32 v171, 0x42080, v170
	global_load_dword v211, v171, s[100:101]
	v_add_u32_e32 v171, 0x44080, v170
	global_load_dword v212, v171, s[100:101]
	v_add_u32_e32 v171, 0x46080, v170
	global_load_dword v213, v171, s[100:101]
	v_add_u32_e32 v171, 0x50080, v170
	global_load_dword v172, v171, s[100:101]
	v_add_u32_e32 v171, 0x52080, v170
	global_load_dword v173, v171, s[100:101]
	v_add_u32_e32 v171, 0x54080, v170
	global_load_dword v174, v171, s[100:101]
	v_add_u32_e32 v171, 0x56080, v170
	global_load_dword v175, v171, s[100:101]
	v_add_u32_e32 v171, 0x60080, v170
	global_load_dword v176, v171, s[100:101]
	v_add_u32_e32 v171, 0x62080, v170
	global_load_dword v177, v171, s[100:101]
	v_add_u32_e32 v171, 0x64080, v170
	global_load_dword v178, v171, s[100:101]
	v_add_u32_e32 v171, 0x66080, v170
	global_load_dword v179, v171, s[100:101]
	v_add_u32_e32 v171, 0x70080, v170
	global_load_dword v132, v171, s[100:101]
	v_add_u32_e32 v171, 0x72080, v170
	global_load_dword v133, v171, s[100:101]
	v_add_u32_e32 v171, 0x74080, v170
	global_load_dword v134, v171, s[100:101]
	global_load_dword v58, v[68:69], off
	v_add_u32_e32 v32, s38, v36
	v_mul_hi_i32 v33, v32, s0
	v_lshrrev_b32_e32 v34, 31, v33
	v_ashrrev_i32_e32 v33, 11, v33
	v_add_u32_e32 v54, v33, v34
	v_mad_i32_i24 v55, v54, s1, v32
	v_cmp_lt_i32_e64 s[42:43], s37, v55
	s_cbranch_vccnz .LBB0_1345
	s_and_saveexec_b64 s[6:7], s[42:43]
	s_xor_b64 s[6:7], exec, s[6:7]
	v_lshlrev_b32_e32 v32, 13, v54
	s_movk_i32 s10, 0xff00
	v_add3_u32 v32, v32, v55, s10
	s_or_saveexec_b64 s[6:7], s[6:7]
	v_mov_b64_e32 v[34:35], s[76:77]
	s_xor_b64 exec, exec, s[6:7]
	v_lshl_add_u32 v32, v54, 8, v55
	v_mov_b64_e32 v[34:35], s[12:13]
	s_or_b64 exec, exec, s[6:7]
	s_mov_b64 s[6:7], 0

; DI int crow(int i, int h) { return (i & 3) + 8 * (i >> 2) + 4 * h; }
; DI const float* xrow(CP p, const Ptrs& w, int l, int tok) {
;   int b = tok / TPB, i = tok - b * TPB;
;   if (l == 0) return i < CTXL ? p.in[2] + (size_t)(b * CTXL + i) * DM : p.in[0] + (size_t)(b * 8192 + i - CTXL) * DM;
;   return i < CTXL ? w.xc1 + (size_t)(b * CTXL + i) * DM : p.out + (size_t)(b * 8192 + i - CTXL) * DM;
; DI void phase_out(CP p, const Ptrs& w, int l, bf16_t* sA, bf16_t* sB) {
;     ...
;         int col = n0 + wn * 64 + ni * 32 + r;
;         float gt = gate[col];
; #pragma unroll
;         for (int i = 0; i < 16; ++i) {
;           int ii = ib + wm * 64 + mi * 32 + crow(i, h);
;           const float* src = xrow(p, w, l, b * TPB + ii);
;           float* dstp = isctx ? w.xc1 + (size_t)(b * CTXL + ii) * DM : p.out + (size_t)(b * 8192 + ii - CTXL) * DM;
;           dstp[col] = src[col] + gt * acc[mi][ni][i];
.LBB0_1351:
	v_ashrrev_i32_e32 v33, 31, v32
	v_lshlrev_b64 v[32:33], 13, v[32:33]
	v_lshl_add_u64 v[32:33], v[34:35], 0, v[32:33]
	v_lshl_add_u64 v[32:33], v[32:33], 0, v[66:67]
	v_add_u32_e32 v34, s39, v36
	v_ashrrev_i32_e32 v35, 31, v34
	v_lshlrev_b64 v[34:35], 13, v[34:35]
	v_lshl_add_u64 v[34:35], s[4:5], 0, v[34:35]
	v_lshl_add_u64 v[32:33], v[34:35], 0, v[66:67]
	s_mov_b64 s[6:7], -1
	s_and_b64 vcc, exec, s[40:41]
	s_waitcnt vmcnt(0)
	v_fma_f32 v36, v16, v58, v194
	v_or_b32_e32 v16, v52, v167
	v_add_u32_e32 v34, s38, v16
	v_mul_hi_i32 v35, v34, s0
	global_store_dword v[32:33], v36, off
	v_lshrrev_b32_e32 v36, 31, v35
	v_ashrrev_i32_e32 v35, 11, v35
	v_add_u32_e32 v56, v35, v36
	v_mad_i32_i24 v57, v56, s1, v34
	v_cmp_lt_i32_e64 s[44:45], s37, v57
	s_cbranch_vccnz .LBB0_1357
	s_and_saveexec_b64 s[6:7], s[44:45]
	s_xor_b64 s[6:7], exec, s[6:7]
	v_lshlrev_b32_e32 v34, 13, v56
	s_movk_i32 s10, 0xff00
	v_add3_u32 v34, v34, v57, s10
	s_or_saveexec_b64 s[6:7], s[6:7]
	v_mov_b64_e32 v[36:37], s[76:77]
	s_xor_b64 exec, exec, s[6:7]
	v_lshl_add_u32 v34, v56, 8, v57
	v_mov_b64_e32 v[36:37], s[12:13]
	s_or_b64 exec, exec, s[6:7]
	s_mov_b64 s[6:7], 0

; DI int crow(int i, int h) { return (i & 3) + 8 * (i >> 2) + 4 * h; }
; DI const float* xrow(CP p, const Ptrs& w, int l, int tok) {
;   int b = tok / TPB, i = tok - b * TPB;
;   if (l == 0) return i < CTXL ? p.in[2] + (size_t)(b * CTXL + i) * DM : p.in[0] + (size_t)(b * 8192 + i - CTXL) * DM;
;   return i < CTXL ? w.xc1 + (size_t)(b * CTXL + i) * DM : p.out + (size_t)(b * 8192 + i - CTXL) * DM;
; DI void phase_out(CP p, const Ptrs& w, int l, bf16_t* sA, bf16_t* sB) {
;     ...
;         int col = n0 + wn * 64 + ni * 32 + r;
;         float gt = gate[col];
; #pragma unroll
;         for (int i = 0; i < 16; ++i) {
;           int ii = ib + wm * 64 + mi * 32 + crow(i, h);
;           const float* src = xrow(p, w, l, b * TPB + ii);
;           float* dstp = isctx ? w.xc1 + (size_t)(b * CTXL + ii) * DM : p.out + (size_t)(b * 8192 + ii - CTXL) * DM;
;           dstp[col] = src[col] + gt * acc[mi][ni][i];
.LBB0_1363:
	v_ashrrev_i32_e32 v35, 31, v34
	v_lshlrev_b64 v[34:35], 13, v[34:35]
	v_lshl_add_u64 v[34:35], v[36:37], 0, v[34:35]
	v_lshl_add_u64 v[34:35], v[34:35], 0, v[66:67]
	v_add_u32_e32 v36, s39, v16
	v_ashrrev_i32_e32 v37, 31, v36
	v_lshlrev_b64 v[36:37], 13, v[36:37]
	v_lshl_add_u64 v[36:37], s[4:5], 0, v[36:37]
	v_or_b32_e32 v38, v52, v180
	s_mov_b64 s[6:7], -1
	s_and_b64 vcc, exec, s[40:41]
	s_waitcnt vmcnt(1)
	v_fma_f32 v34, v17, v58, v195
	v_lshl_add_u64 v[16:17], v[36:37], 0, v[66:67]
	global_store_dword v[16:17], v34, off
	v_add_u32_e32 v34, s38, v38
	v_mul_hi_i32 v35, v34, s0
	v_lshrrev_b32_e32 v36, 31, v35
	v_ashrrev_i32_e32 v35, 11, v35
	v_add_u32_e32 v59, v35, v36
	v_mad_i32_i24 v60, v59, s1, v34
	v_cmp_lt_i32_e64 s[46:47], s37, v60
	s_cbranch_vccnz .LBB0_1369
	s_and_saveexec_b64 s[6:7], s[46:47]
	s_xor_b64 s[6:7], exec, s[6:7]
	v_lshlrev_b32_e32 v34, 13, v59
	s_movk_i32 s10, 0xff00
	v_add3_u32 v34, v34, v60, s10
	s_or_saveexec_b64 s[6:7], s[6:7]
	v_mov_b64_e32 v[36:37], s[76:77]
	s_xor_b64 exec, exec, s[6:7]
	v_lshl_add_u32 v34, v59, 8, v60
	v_mov_b64_e32 v[36:37], s[12:13]
	s_or_b64 exec, exec, s[6:7]
	s_mov_b64 s[6:7], 0

; DI int crow(int i, int h) { return (i & 3) + 8 * (i >> 2) + 4 * h; }
; DI const float* xrow(CP p, const Ptrs& w, int l, int tok) {
;   int b = tok / TPB, i = tok - b * TPB;
;   if (l == 0) return i < CTXL ? p.in[2] + (size_t)(b * CTXL + i) * DM : p.in[0] + (size_t)(b * 8192 + i - CTXL) * DM;
;   return i < CTXL ? w.xc1 + (size_t)(b * CTXL + i) * DM : p.out + (size_t)(b * 8192 + i - CTXL) * DM;
; DI void phase_out(CP p, const Ptrs& w, int l, bf16_t* sA, bf16_t* sB) {
;     ...
;         int col = n0 + wn * 64 + ni * 32 + r;
;         float gt = gate[col];
; #pragma unroll
;         for (int i = 0; i < 16; ++i) {
;           int ii = ib + wm * 64 + mi * 32 + crow(i, h);
;           const float* src = xrow(p, w, l, b * TPB + ii);
;           float* dstp = isctx ? w.xc1 + (size_t)(b * CTXL + ii) * DM : p.out + (size_t)(b * 8192 + ii - CTXL) * DM;
;           dstp[col] = src[col] + gt * acc[mi][ni][i];
.LBB0_1375:
	v_ashrrev_i32_e32 v35, 31, v34
	v_lshlrev_b64 v[34:35], 13, v[34:35]
	v_lshl_add_u64 v[34:35], v[36:37], 0, v[34:35]
	v_lshl_add_u64 v[34:35], v[34:35], 0, v[66:67]
	v_add_u32_e32 v36, s39, v38
	v_ashrrev_i32_e32 v37, 31, v36
	v_lshlrev_b64 v[36:37], 13, v[36:37]
	v_lshl_add_u64 v[36:37], s[4:5], 0, v[36:37]
	v_lshl_add_u64 v[34:35], v[36:37], 0, v[66:67]
	s_mov_b64 s[6:7], -1
	s_and_b64 vcc, exec, s[40:41]
	s_waitcnt vmcnt(2)
	v_fma_f32 v38, v18, v58, v196
	v_or_b32_e32 v18, v52, v181
	v_add_u32_e32 v36, s38, v18
	v_mul_hi_i32 v37, v36, s0
	global_store_dword v[34:35], v38, off
	v_lshrrev_b32_e32 v38, 31, v37
	v_ashrrev_i32_e32 v37, 11, v37
	v_add_u32_e32 v61, v37, v38
	v_mad_i32_i24 v62, v61, s1, v36
	v_cmp_lt_i32_e64 s[48:49], s37, v62
	s_cbranch_vccnz .LBB0_1381
	s_and_saveexec_b64 s[6:7], s[48:49]
	s_xor_b64 s[6:7], exec, s[6:7]
	v_lshlrev_b32_e32 v36, 13, v61
	s_movk_i32 s10, 0xff00
	v_add3_u32 v36, v36, v62, s10
	s_or_saveexec_b64 s[6:7], s[6:7]
	v_mov_b64_e32 v[38:39], s[76:77]
	s_xor_b64 exec, exec, s[6:7]
	v_lshl_add_u32 v36, v61, 8, v62
	v_mov_b64_e32 v[38:39], s[12:13]
	s_or_b64 exec, exec, s[6:7]
	s_mov_b64 s[6:7], 0

; DI int crow(int i, int h) { return (i & 3) + 8 * (i >> 2) + 4 * h; }
; DI const float* xrow(CP p, const Ptrs& w, int l, int tok) {
;   int b = tok / TPB, i = tok - b * TPB;
;   if (l == 0) return i < CTXL ? p.in[2] + (size_t)(b * CTXL + i) * DM : p.in[0] + (size_t)(b * 8192 + i - CTXL) * DM;
;   return i < CTXL ? w.xc1 + (size_t)(b * CTXL + i) * DM : p.out + (size_t)(b * 8192 + i - CTXL) * DM;
; DI void phase_out(CP p, const Ptrs& w, int l, bf16_t* sA, bf16_t* sB) {
;     ...
;         int col = n0 + wn * 64 + ni * 32 + r;
;         float gt = gate[col];
; #pragma unroll
;         for (int i = 0; i < 16; ++i) {
;           int ii = ib + wm * 64 + mi * 32 + crow(i, h);
;           const float* src = xrow(p, w, l, b * TPB + ii);
;           float* dstp = isctx ? w.xc1 + (size_t)(b * CTXL + ii) * DM : p.out + (size_t)(b * 8192 + ii - CTXL) * DM;
;           dstp[col] = src[col] + gt * acc[mi][ni][i];
.LBB0_1387:
	v_ashrrev_i32_e32 v37, 31, v36
	v_lshlrev_b64 v[36:37], 13, v[36:37]
	v_lshl_add_u64 v[36:37], v[38:39], 0, v[36:37]
	v_lshl_add_u64 v[36:37], v[36:37], 0, v[66:67]
	v_add_u32_e32 v38, s39, v18
	v_ashrrev_i32_e32 v39, 31, v38
	v_lshlrev_b64 v[38:39], 13, v[38:39]
	v_lshl_add_u64 v[38:39], s[4:5], 0, v[38:39]
	v_or_b32_e32 v40, v52, v182
	s_mov_b64 s[6:7], -1
	s_and_b64 vcc, exec, s[40:41]
	s_waitcnt vmcnt(3)
	v_fma_f32 v36, v19, v58, v197
	v_lshl_add_u64 v[18:19], v[38:39], 0, v[66:67]
	global_store_dword v[18:19], v36, off
	v_add_u32_e32 v36, s38, v40
	v_mul_hi_i32 v37, v36, s0
	v_lshrrev_b32_e32 v38, 31, v37
	v_ashrrev_i32_e32 v37, 11, v37
	v_add_u32_e32 v63, v37, v38
	v_mad_i32_i24 v68, v63, s1, v36
	v_cmp_lt_i32_e64 s[50:51], s37, v68
	s_cbranch_vccnz .LBB0_1393
	s_and_saveexec_b64 s[6:7], s[50:51]
	s_xor_b64 s[6:7], exec, s[6:7]
	v_lshlrev_b32_e32 v36, 13, v63
	s_movk_i32 s10, 0xff00
	v_add3_u32 v36, v36, v68, s10
	s_or_saveexec_b64 s[6:7], s[6:7]
	v_mov_b64_e32 v[38:39], s[76:77]
	s_xor_b64 exec, exec, s[6:7]
	v_lshl_add_u32 v36, v63, 8, v68
	v_mov_b64_e32 v[38:39], s[12:13]
	s_or_b64 exec, exec, s[6:7]
	s_mov_b64 s[6:7], 0

; DI int crow(int i, int h) { return (i & 3) + 8 * (i >> 2) + 4 * h; }
; DI const float* xrow(CP p, const Ptrs& w, int l, int tok) {
;   int b = tok / TPB, i = tok - b * TPB;
;   if (l == 0) return i < CTXL ? p.in[2] + (size_t)(b * CTXL + i) * DM : p.in[0] + (size_t)(b * 8192 + i - CTXL) * DM;
;   return i < CTXL ? w.xc1 + (size_t)(b * CTXL + i) * DM : p.out + (size_t)(b * 8192 + i - CTXL) * DM;
; DI void phase_out(CP p, const Ptrs& w, int l, bf16_t* sA, bf16_t* sB) {
;     ...
;         int col = n0 + wn * 64 + ni * 32 + r;
;         float gt = gate[col];
; #pragma unroll
;         for (int i = 0; i < 16; ++i) {
;           int ii = ib + wm * 64 + mi * 32 + crow(i, h);
;           const float* src = xrow(p, w, l, b * TPB + ii);
;           float* dstp = isctx ? w.xc1 + (size_t)(b * CTXL + ii) * DM : p.out + (size_t)(b * 8192 + ii - CTXL) * DM;
;           dstp[col] = src[col] + gt * acc[mi][ni][i];
.LBB0_1399:
	v_ashrrev_i32_e32 v37, 31, v36
	v_lshlrev_b64 v[36:37], 13, v[36:37]
	v_lshl_add_u64 v[36:37], v[38:39], 0, v[36:37]
	v_lshl_add_u64 v[36:37], v[36:37], 0, v[66:67]
	v_add_u32_e32 v38, s39, v40
	v_ashrrev_i32_e32 v39, 31, v38
	v_lshlrev_b64 v[38:39], 13, v[38:39]
	v_lshl_add_u64 v[38:39], s[4:5], 0, v[38:39]
	v_lshl_add_u64 v[36:37], v[38:39], 0, v[66:67]
	s_mov_b64 s[6:7], -1
	s_and_b64 vcc, exec, s[40:41]
	s_waitcnt vmcnt(4)
	v_fma_f32 v40, v20, v58, v198
	v_or_b32_e32 v20, v52, v183
	v_add_u32_e32 v38, s38, v20
	v_mul_hi_i32 v39, v38, s0
	global_store_dword v[36:37], v40, off
	v_lshrrev_b32_e32 v40, 31, v39
	v_ashrrev_i32_e32 v39, 11, v39
	v_add_u32_e32 v69, v39, v40
	v_mad_i32_i24 v70, v69, s1, v38
	v_cmp_lt_i32_e64 s[52:53], s37, v70
	s_cbranch_vccnz .LBB0_1405
	s_and_saveexec_b64 s[6:7], s[52:53]
	s_xor_b64 s[6:7], exec, s[6:7]
	v_lshlrev_b32_e32 v38, 13, v69
	s_movk_i32 s10, 0xff00
	v_add3_u32 v38, v38, v70, s10
	s_or_saveexec_b64 s[6:7], s[6:7]
	v_mov_b64_e32 v[40:41], s[76:77]
	s_xor_b64 exec, exec, s[6:7]
	v_lshl_add_u32 v38, v69, 8, v70
	v_mov_b64_e32 v[40:41], s[12:13]
	s_or_b64 exec, exec, s[6:7]
	s_mov_b64 s[6:7], 0

; DI int crow(int i, int h) { return (i & 3) + 8 * (i >> 2) + 4 * h; }
; DI const float* xrow(CP p, const Ptrs& w, int l, int tok) {
;   int b = tok / TPB, i = tok - b * TPB;
;   if (l == 0) return i < CTXL ? p.in[2] + (size_t)(b * CTXL + i) * DM : p.in[0] + (size_t)(b * 8192 + i - CTXL) * DM;
;   return i < CTXL ? w.xc1 + (size_t)(b * CTXL + i) * DM : p.out + (size_t)(b * 8192 + i - CTXL) * DM;
; DI void phase_out(CP p, const Ptrs& w, int l, bf16_t* sA, bf16_t* sB) {
;     ...
;         int col = n0 + wn * 64 + ni * 32 + r;
;         float gt = gate[col];
; #pragma unroll
;         for (int i = 0; i < 16; ++i) {
;           int ii = ib + wm * 64 + mi * 32 + crow(i, h);
;           const float* src = xrow(p, w, l, b * TPB + ii);
;           float* dstp = isctx ? w.xc1 + (size_t)(b * CTXL + ii) * DM : p.out + (size_t)(b * 8192 + ii - CTXL) * DM;
;           dstp[col] = src[col] + gt * acc[mi][ni][i];
.LBB0_1411:
	v_ashrrev_i32_e32 v39, 31, v38
	v_lshlrev_b64 v[38:39], 13, v[38:39]
	v_lshl_add_u64 v[38:39], v[40:41], 0, v[38:39]
	v_lshl_add_u64 v[38:39], v[38:39], 0, v[66:67]
	v_add_u32_e32 v40, s39, v20
	v_ashrrev_i32_e32 v41, 31, v40
	v_lshlrev_b64 v[40:41], 13, v[40:41]
	v_lshl_add_u64 v[40:41], s[4:5], 0, v[40:41]
	v_or_b32_e32 v42, v52, v184
	s_mov_b64 s[6:7], -1
	s_and_b64 vcc, exec, s[40:41]
	s_waitcnt vmcnt(5)
	v_fma_f32 v38, v21, v58, v199
	v_lshl_add_u64 v[20:21], v[40:41], 0, v[66:67]
	global_store_dword v[20:21], v38, off
	v_add_u32_e32 v38, s38, v42
	v_mul_hi_i32 v39, v38, s0
	v_lshrrev_b32_e32 v40, 31, v39
	v_ashrrev_i32_e32 v39, 11, v39
	v_add_u32_e32 v71, v39, v40
	v_mad_i32_i24 v72, v71, s1, v38
	v_cmp_lt_i32_e64 s[54:55], s37, v72
	s_cbranch_vccnz .LBB0_1417
	s_and_saveexec_b64 s[6:7], s[54:55]
	s_xor_b64 s[6:7], exec, s[6:7]
	v_lshlrev_b32_e32 v38, 13, v71
	s_movk_i32 s10, 0xff00
	v_add3_u32 v38, v38, v72, s10
	s_or_saveexec_b64 s[6:7], s[6:7]
	v_mov_b64_e32 v[40:41], s[76:77]
	s_xor_b64 exec, exec, s[6:7]
	v_lshl_add_u32 v38, v71, 8, v72
	v_mov_b64_e32 v[40:41], s[12:13]
	s_or_b64 exec, exec, s[6:7]
	s_mov_b64 s[6:7], 0

; DI int crow(int i, int h) { return (i & 3) + 8 * (i >> 2) + 4 * h; }
; DI const float* xrow(CP p, const Ptrs& w, int l, int tok) {
;   int b = tok / TPB, i = tok - b * TPB;
;   if (l == 0) return i < CTXL ? p.in[2] + (size_t)(b * CTXL + i) * DM : p.in[0] + (size_t)(b * 8192 + i - CTXL) * DM;
;   return i < CTXL ? w.xc1 + (size_t)(b * CTXL + i) * DM : p.out + (size_t)(b * 8192 + i - CTXL) * DM;
; DI void phase_out(CP p, const Ptrs& w, int l, bf16_t* sA, bf16_t* sB) {
;     ...
;         int col = n0 + wn * 64 + ni * 32 + r;
;         float gt = gate[col];
; #pragma unroll
;         for (int i = 0; i < 16; ++i) {
;           int ii = ib + wm * 64 + mi * 32 + crow(i, h);
;           const float* src = xrow(p, w, l, b * TPB + ii);
;           float* dstp = isctx ? w.xc1 + (size_t)(b * CTXL + ii) * DM : p.out + (size_t)(b * 8192 + ii - CTXL) * DM;
;           dstp[col] = src[col] + gt * acc[mi][ni][i];
.LBB0_1423:
	v_ashrrev_i32_e32 v39, 31, v38
	v_lshlrev_b64 v[38:39], 13, v[38:39]
	v_lshl_add_u64 v[38:39], v[40:41], 0, v[38:39]
	v_lshl_add_u64 v[38:39], v[38:39], 0, v[66:67]
	v_add_u32_e32 v40, s39, v42
	v_ashrrev_i32_e32 v41, 31, v40
	v_lshlrev_b64 v[40:41], 13, v[40:41]
	v_lshl_add_u64 v[40:41], s[4:5], 0, v[40:41]
	v_lshl_add_u64 v[38:39], v[40:41], 0, v[66:67]
	s_mov_b64 s[6:7], -1
	s_and_b64 vcc, exec, s[40:41]
	s_waitcnt vmcnt(6)
	v_fma_f32 v42, v22, v58, v200
	v_or_b32_e32 v22, v52, v185
	v_add_u32_e32 v40, s38, v22
	v_mul_hi_i32 v41, v40, s0
	global_store_dword v[38:39], v42, off
	v_lshrrev_b32_e32 v42, 31, v41
	v_ashrrev_i32_e32 v41, 11, v41
	v_add_u32_e32 v73, v41, v42
	v_mad_i32_i24 v74, v73, s1, v40
	v_cmp_lt_i32_e64 s[56:57], s37, v74
	s_cbranch_vccnz .LBB0_1429
	s_and_saveexec_b64 s[6:7], s[56:57]
	s_xor_b64 s[6:7], exec, s[6:7]
	v_lshlrev_b32_e32 v40, 13, v73
	s_movk_i32 s10, 0xff00
	v_add3_u32 v40, v40, v74, s10
	s_or_saveexec_b64 s[6:7], s[6:7]
	v_mov_b64_e32 v[42:43], s[76:77]
	s_xor_b64 exec, exec, s[6:7]
	v_lshl_add_u32 v40, v73, 8, v74
	v_mov_b64_e32 v[42:43], s[12:13]
	s_or_b64 exec, exec, s[6:7]
	s_mov_b64 s[6:7], 0

; DI int crow(int i, int h) { return (i & 3) + 8 * (i >> 2) + 4 * h; }
; DI const float* xrow(CP p, const Ptrs& w, int l, int tok) {
;   int b = tok / TPB, i = tok - b * TPB;
;   if (l == 0) return i < CTXL ? p.in[2] + (size_t)(b * CTXL + i) * DM : p.in[0] + (size_t)(b * 8192 + i - CTXL) * DM;
;   return i < CTXL ? w.xc1 + (size_t)(b * CTXL + i) * DM : p.out + (size_t)(b * 8192 + i - CTXL) * DM;
; DI void phase_out(CP p, const Ptrs& w, int l, bf16_t* sA, bf16_t* sB) {
;     ...
;         int col = n0 + wn * 64 + ni * 32 + r;
;         float gt = gate[col];
; #pragma unroll
;         for (int i = 0; i < 16; ++i) {
;           int ii = ib + wm * 64 + mi * 32 + crow(i, h);
;           const float* src = xrow(p, w, l, b * TPB + ii);
;           float* dstp = isctx ? w.xc1 + (size_t)(b * CTXL + ii) * DM : p.out + (size_t)(b * 8192 + ii - CTXL) * DM;
;           dstp[col] = src[col] + gt * acc[mi][ni][i];
.LBB0_1435:
	v_ashrrev_i32_e32 v41, 31, v40
	v_lshlrev_b64 v[40:41], 13, v[40:41]
	v_lshl_add_u64 v[40:41], v[42:43], 0, v[40:41]
	v_lshl_add_u64 v[40:41], v[40:41], 0, v[66:67]
	v_add_u32_e32 v42, s39, v22
	v_ashrrev_i32_e32 v43, 31, v42
	v_lshlrev_b64 v[42:43], 13, v[42:43]
	v_lshl_add_u64 v[42:43], s[4:5], 0, v[42:43]
	v_or_b32_e32 v44, v52, v186
	s_mov_b64 s[6:7], -1
	s_and_b64 vcc, exec, s[40:41]
	s_waitcnt vmcnt(7)
	v_fma_f32 v40, v23, v58, v201
	v_lshl_add_u64 v[22:23], v[42:43], 0, v[66:67]
	global_store_dword v[22:23], v40, off
	v_add_u32_e32 v40, s38, v44
	v_mul_hi_i32 v41, v40, s0
	v_lshrrev_b32_e32 v42, 31, v41
	v_ashrrev_i32_e32 v41, 11, v41
	v_add_u32_e32 v75, v41, v42
	v_mad_i32_i24 v76, v75, s1, v40
	v_cmp_lt_i32_e64 s[58:59], s37, v76
	s_cbranch_vccnz .LBB0_1441
	s_and_saveexec_b64 s[6:7], s[58:59]
	s_xor_b64 s[6:7], exec, s[6:7]
	v_lshlrev_b32_e32 v40, 13, v75
	s_movk_i32 s10, 0xff00
	v_add3_u32 v40, v40, v76, s10
	s_or_saveexec_b64 s[6:7], s[6:7]
	v_mov_b64_e32 v[42:43], s[76:77]
	s_xor_b64 exec, exec, s[6:7]
	v_lshl_add_u32 v40, v75, 8, v76
	v_mov_b64_e32 v[42:43], s[12:13]
	s_or_b64 exec, exec, s[6:7]
	s_mov_b64 s[6:7], 0

; DI int crow(int i, int h) { return (i & 3) + 8 * (i >> 2) + 4 * h; }
; DI void phase_out(CP p, const Ptrs& w, int l, bf16_t* sA, bf16_t* sB) {
;     ...
;     for (int mi = 0; mi < 2; ++mi)
; #pragma unroll
;       for (int ni = 0; ni < 2; ++ni) {
;         int col = n0 + wn * 64 + ni * 32 + r;
;         float gt = gate[col];
; #pragma unroll
;         for (int i = 0; i < 16; ++i) {
;           int ii = ib + wm * 64 + mi * 32 + crow(i, h);
;           const float* src = xrow(p, w, l, b * TPB + ii);
;           float* dstp = isctx ? w.xc1 + (size_t)(b * CTXL + ii) * DM : p.out + (size_t)(b * 8192 + ii - CTXL) * DM;
;           dstp[col] = src[col] + gt * acc[mi][ni][i];
;         }
.LBB0_1447:
	v_ashrrev_i32_e32 v41, 31, v40
	v_lshlrev_b64 v[40:41], 13, v[40:41]
	v_lshl_add_u64 v[40:41], v[42:43], 0, v[40:41]
	v_lshl_add_u64 v[40:41], v[40:41], 0, v[66:67]
	v_add_u32_e32 v42, s39, v44
	v_ashrrev_i32_e32 v43, 31, v42
	v_lshlrev_b64 v[42:43], 13, v[42:43]
	v_lshl_add_u64 v[42:43], s[4:5], 0, v[42:43]
	v_lshl_add_u64 v[40:41], v[42:43], 0, v[66:67]
	s_mov_b64 s[6:7], -1
	s_and_b64 vcc, exec, s[40:41]
	s_waitcnt vmcnt(8)
	v_fma_f32 v44, v24, v58, v202
	v_or_b32_e32 v24, v52, v187
	v_add_u32_e32 v42, s38, v24
	v_mul_hi_i32 v43, v42, s0
	global_store_dword v[40:41], v44, off
	v_lshrrev_b32_e32 v44, 31, v43
	v_ashrrev_i32_e32 v43, 11, v43
	v_add_u32_e32 v77, v43, v44
	v_mad_i32_i24 v78, v77, s1, v42
	v_cmp_lt_i32_e64 s[60:61], s37, v78
	s_cbranch_vccnz .LBB0_1453
	s_and_saveexec_b64 s[6:7], s[60:61]
	s_xor_b64 s[6:7], exec, s[6:7]
	v_lshlrev_b32_e32 v42, 13, v77
	s_movk_i32 s10, 0xff00
	v_add3_u32 v42, v42, v78, s10
	s_or_saveexec_b64 s[6:7], s[6:7]
	v_mov_b64_e32 v[44:45], s[76:77]
	s_xor_b64 exec, exec, s[6:7]
	v_lshl_add_u32 v42, v77, 8, v78
	v_mov_b64_e32 v[44:45], s[12:13]
	s_or_b64 exec, exec, s[6:7]
	s_mov_b64 s[6:7], 0

; DI int crow(int i, int h) { return (i & 3) + 8 * (i >> 2) + 4 * h; }
; DI void phase_out(CP p, const Ptrs& w, int l, bf16_t* sA, bf16_t* sB) {
;     ...
;     for (int mi = 0; mi < 2; ++mi)
; #pragma unroll
;       for (int ni = 0; ni < 2; ++ni) {
;         int col = n0 + wn * 64 + ni * 32 + r;
;         float gt = gate[col];
; #pragma unroll
;         for (int i = 0; i < 16; ++i) {
;           int ii = ib + wm * 64 + mi * 32 + crow(i, h);
;           const float* src = xrow(p, w, l, b * TPB + ii);
;           float* dstp = isctx ? w.xc1 + (size_t)(b * CTXL + ii) * DM : p.out + (size_t)(b * 8192 + ii - CTXL) * DM;
;           dstp[col] = src[col] + gt * acc[mi][ni][i];
;         }
.LBB0_1459:
	v_ashrrev_i32_e32 v43, 31, v42
	v_lshlrev_b64 v[42:43], 13, v[42:43]
	v_lshl_add_u64 v[42:43], v[44:45], 0, v[42:43]
	v_lshl_add_u64 v[42:43], v[42:43], 0, v[66:67]
	v_add_u32_e32 v44, s39, v24
	v_ashrrev_i32_e32 v45, 31, v44
	v_lshlrev_b64 v[44:45], 13, v[44:45]
	v_lshl_add_u64 v[44:45], s[4:5], 0, v[44:45]
	v_or_b32_e32 v46, v52, v188
	s_mov_b64 s[6:7], -1
	s_and_b64 vcc, exec, s[40:41]
	s_waitcnt vmcnt(9)
	v_fma_f32 v42, v25, v58, v203
	v_lshl_add_u64 v[24:25], v[44:45], 0, v[66:67]
	global_store_dword v[24:25], v42, off
	v_add_u32_e32 v42, s38, v46
	v_mul_hi_i32 v43, v42, s0
	v_lshrrev_b32_e32 v44, 31, v43
	v_ashrrev_i32_e32 v43, 11, v43
	v_add_u32_e32 v79, v43, v44
	v_mad_i32_i24 v80, v79, s1, v42
	v_cmp_lt_i32_e64 s[62:63], s37, v80
	s_cbranch_vccnz .LBB0_1465
	s_and_saveexec_b64 s[6:7], s[62:63]
	s_xor_b64 s[6:7], exec, s[6:7]
	v_lshlrev_b32_e32 v42, 13, v79
	s_movk_i32 s10, 0xff00
	v_add3_u32 v42, v42, v80, s10
	s_or_saveexec_b64 s[6:7], s[6:7]
	v_mov_b64_e32 v[44:45], s[76:77]
	s_xor_b64 exec, exec, s[6:7]
	v_lshl_add_u32 v42, v79, 8, v80
	v_mov_b64_e32 v[44:45], s[12:13]
	s_or_b64 exec, exec, s[6:7]
	s_mov_b64 s[6:7], 0

; DI int crow(int i, int h) { return (i & 3) + 8 * (i >> 2) + 4 * h; }
; DI void phase_out(CP p, const Ptrs& w, int l, bf16_t* sA, bf16_t* sB) {
;     ...
;     for (int mi = 0; mi < 2; ++mi)
; #pragma unroll
;       for (int ni = 0; ni < 2; ++ni) {
;         int col = n0 + wn * 64 + ni * 32 + r;
;         float gt = gate[col];
; #pragma unroll
;         for (int i = 0; i < 16; ++i) {
;           int ii = ib + wm * 64 + mi * 32 + crow(i, h);
;           const float* src = xrow(p, w, l, b * TPB + ii);
;           float* dstp = isctx ? w.xc1 + (size_t)(b * CTXL + ii) * DM : p.out + (size_t)(b * 8192 + ii - CTXL) * DM;
;           dstp[col] = src[col] + gt * acc[mi][ni][i];
;         }
.LBB0_1471:
	v_ashrrev_i32_e32 v43, 31, v42
	v_lshlrev_b64 v[42:43], 13, v[42:43]
	v_lshl_add_u64 v[42:43], v[44:45], 0, v[42:43]
	v_lshl_add_u64 v[42:43], v[42:43], 0, v[66:67]
	v_add_u32_e32 v44, s39, v46
	v_ashrrev_i32_e32 v45, 31, v44
	v_lshlrev_b64 v[44:45], 13, v[44:45]
	v_lshl_add_u64 v[44:45], s[4:5], 0, v[44:45]
	v_lshl_add_u64 v[42:43], v[44:45], 0, v[66:67]
	s_mov_b64 s[6:7], -1
	s_and_b64 vcc, exec, s[40:41]
	s_waitcnt vmcnt(10)
	v_fma_f32 v46, v26, v58, v204
	v_or_b32_e32 v26, v52, v189
	v_add_u32_e32 v44, s38, v26
	v_mul_hi_i32 v45, v44, s0
	global_store_dword v[42:43], v46, off
	v_lshrrev_b32_e32 v46, 31, v45
	v_ashrrev_i32_e32 v45, 11, v45
	v_add_u32_e32 v81, v45, v46
	v_mad_i32_i24 v82, v81, s1, v44
	v_cmp_lt_i32_e64 s[64:65], s37, v82
	s_cbranch_vccnz .LBB0_1477
	s_and_saveexec_b64 s[6:7], s[64:65]
	s_xor_b64 s[6:7], exec, s[6:7]
	v_lshlrev_b32_e32 v44, 13, v81
	s_movk_i32 s10, 0xff00
	v_add3_u32 v44, v44, v82, s10
	s_or_saveexec_b64 s[6:7], s[6:7]
	v_mov_b64_e32 v[46:47], s[76:77]
	s_xor_b64 exec, exec, s[6:7]
	v_lshl_add_u32 v44, v81, 8, v82
	v_mov_b64_e32 v[46:47], s[12:13]
	s_or_b64 exec, exec, s[6:7]
	s_mov_b64 s[6:7], 0

; DI int crow(int i, int h) { return (i & 3) + 8 * (i >> 2) + 4 * h; }
; DI void phase_out(CP p, const Ptrs& w, int l, bf16_t* sA, bf16_t* sB) {
;     ...
;     for (int mi = 0; mi < 2; ++mi)
; #pragma unroll
;       for (int ni = 0; ni < 2; ++ni) {
;         int col = n0 + wn * 64 + ni * 32 + r;
;         float gt = gate[col];
; #pragma unroll
;         for (int i = 0; i < 16; ++i) {
;           int ii = ib + wm * 64 + mi * 32 + crow(i, h);
;           const float* src = xrow(p, w, l, b * TPB + ii);
;           float* dstp = isctx ? w.xc1 + (size_t)(b * CTXL + ii) * DM : p.out + (size_t)(b * 8192 + ii - CTXL) * DM;
;           dstp[col] = src[col] + gt * acc[mi][ni][i];
;         }
.LBB0_1483:
	v_ashrrev_i32_e32 v45, 31, v44
	v_lshlrev_b64 v[44:45], 13, v[44:45]
	v_lshl_add_u64 v[44:45], v[46:47], 0, v[44:45]
	v_lshl_add_u64 v[44:45], v[44:45], 0, v[66:67]
	v_add_u32_e32 v46, s39, v26
	v_ashrrev_i32_e32 v47, 31, v46
	v_lshlrev_b64 v[46:47], 13, v[46:47]
	v_lshl_add_u64 v[46:47], s[4:5], 0, v[46:47]
	v_or_b32_e32 v50, v52, v190
	s_mov_b64 s[6:7], -1
	s_and_b64 vcc, exec, s[40:41]
	s_waitcnt vmcnt(11)
	v_fma_f32 v44, v27, v58, v205
	v_lshl_add_u64 v[26:27], v[46:47], 0, v[66:67]
	global_store_dword v[26:27], v44, off
	v_add_u32_e32 v44, s38, v50
	v_mul_hi_i32 v45, v44, s0
	v_lshrrev_b32_e32 v46, 31, v45
	v_ashrrev_i32_e32 v45, 11, v45
	v_add_u32_e32 v83, v45, v46
	v_mad_i32_i24 v84, v83, s1, v44
	v_cmp_lt_i32_e64 s[66:67], s37, v84
	s_cbranch_vccnz .LBB0_1489
	s_and_saveexec_b64 s[6:7], s[66:67]
	s_xor_b64 s[6:7], exec, s[6:7]
	v_lshlrev_b32_e32 v44, 13, v83
	s_movk_i32 s10, 0xff00
	v_add3_u32 v44, v44, v84, s10
	s_or_saveexec_b64 s[6:7], s[6:7]
	v_mov_b64_e32 v[46:47], s[76:77]
	s_xor_b64 exec, exec, s[6:7]
	v_lshl_add_u32 v44, v83, 8, v84
	v_mov_b64_e32 v[46:47], s[12:13]
	s_or_b64 exec, exec, s[6:7]
	s_mov_b64 s[6:7], 0

; DI int crow(int i, int h) { return (i & 3) + 8 * (i >> 2) + 4 * h; }
; DI void phase_out(CP p, const Ptrs& w, int l, bf16_t* sA, bf16_t* sB) {
;     ...
;     for (int mi = 0; mi < 2; ++mi)
; #pragma unroll
;       for (int ni = 0; ni < 2; ++ni) {
;         int col = n0 + wn * 64 + ni * 32 + r;
;         float gt = gate[col];
; #pragma unroll
;         for (int i = 0; i < 16; ++i) {
;           int ii = ib + wm * 64 + mi * 32 + crow(i, h);
;           const float* src = xrow(p, w, l, b * TPB + ii);
;           float* dstp = isctx ? w.xc1 + (size_t)(b * CTXL + ii) * DM : p.out + (size_t)(b * 8192 + ii - CTXL) * DM;
;           dstp[col] = src[col] + gt * acc[mi][ni][i];
;         }
.LBB0_1495:
	v_ashrrev_i32_e32 v45, 31, v44
	v_lshlrev_b64 v[44:45], 13, v[44:45]
	v_lshl_add_u64 v[44:45], v[46:47], 0, v[44:45]
	v_lshl_add_u64 v[44:45], v[44:45], 0, v[66:67]
	v_add_u32_e32 v46, s39, v50
	v_ashrrev_i32_e32 v47, 31, v46
	v_lshlrev_b64 v[46:47], 13, v[46:47]
	v_lshl_add_u64 v[46:47], s[4:5], 0, v[46:47]
	v_lshl_add_u64 v[44:45], v[46:47], 0, v[66:67]
	s_mov_b64 s[6:7], -1
	s_and_b64 vcc, exec, s[40:41]
	s_waitcnt vmcnt(12)
	v_fma_f32 v50, v28, v58, v206
	v_or_b32_e32 v28, v52, v191
	v_add_u32_e32 v46, s38, v28
	v_mul_hi_i32 v47, v46, s0
	global_store_dword v[44:45], v50, off
	v_lshrrev_b32_e32 v50, 31, v47
	v_ashrrev_i32_e32 v47, 11, v47
	v_add_u32_e32 v85, v47, v50
	v_mad_i32_i24 v86, v85, s1, v46
	v_cmp_lt_i32_e64 s[68:69], s37, v86
	s_cbranch_vccnz .LBB0_1501
	s_and_saveexec_b64 s[6:7], s[68:69]
	s_xor_b64 s[6:7], exec, s[6:7]
	v_lshlrev_b32_e32 v46, 13, v85
	s_movk_i32 s10, 0xff00
	v_add3_u32 v46, v46, v86, s10
	s_or_saveexec_b64 s[6:7], s[6:7]
	v_mov_b64_e32 v[50:51], s[76:77]
	s_xor_b64 exec, exec, s[6:7]
	v_lshl_add_u32 v46, v85, 8, v86
	v_mov_b64_e32 v[50:51], s[12:13]
	s_or_b64 exec, exec, s[6:7]
	s_mov_b64 s[6:7], 0

; DI int crow(int i, int h) { return (i & 3) + 8 * (i >> 2) + 4 * h; }
; DI void phase_out(CP p, const Ptrs& w, int l, bf16_t* sA, bf16_t* sB) {
;     ...
;     for (int mi = 0; mi < 2; ++mi)
; #pragma unroll
;       for (int ni = 0; ni < 2; ++ni) {
;         int col = n0 + wn * 64 + ni * 32 + r;
;         float gt = gate[col];
; #pragma unroll
;         for (int i = 0; i < 16; ++i) {
;           int ii = ib + wm * 64 + mi * 32 + crow(i, h);
;           const float* src = xrow(p, w, l, b * TPB + ii);
;           float* dstp = isctx ? w.xc1 + (size_t)(b * CTXL + ii) * DM : p.out + (size_t)(b * 8192 + ii - CTXL) * DM;
;           dstp[col] = src[col] + gt * acc[mi][ni][i];
;         }
.LBB0_1507:
	v_ashrrev_i32_e32 v47, 31, v46
	v_lshlrev_b64 v[46:47], 13, v[46:47]
	v_lshl_add_u64 v[46:47], v[50:51], 0, v[46:47]
	v_lshl_add_u64 v[46:47], v[46:47], 0, v[66:67]
	v_add_u32_e32 v50, s39, v28
	v_ashrrev_i32_e32 v51, 31, v50
	v_lshlrev_b64 v[50:51], 13, v[50:51]
	v_lshl_add_u64 v[50:51], s[4:5], 0, v[50:51]
	v_or_b32_e32 v53, v52, v192
	s_mov_b64 s[6:7], -1
	s_and_b64 vcc, exec, s[40:41]
	s_waitcnt vmcnt(13)
	v_fma_f32 v46, v29, v58, v207
	v_lshl_add_u64 v[28:29], v[50:51], 0, v[66:67]
	global_store_dword v[28:29], v46, off
	v_add_u32_e32 v46, s38, v53
	v_mul_hi_i32 v47, v46, s0
	v_lshrrev_b32_e32 v50, 31, v47
	v_ashrrev_i32_e32 v47, 11, v47
	v_add_u32_e32 v87, v47, v50
	v_mad_i32_i24 v88, v87, s1, v46
	v_cmp_lt_i32_e64 s[70:71], s37, v88
	s_cbranch_vccnz .LBB0_1513
	s_and_saveexec_b64 s[6:7], s[70:71]
	s_xor_b64 s[6:7], exec, s[6:7]
	v_lshlrev_b32_e32 v46, 13, v87
	s_movk_i32 s10, 0xff00
	v_add3_u32 v46, v46, v88, s10
	s_or_saveexec_b64 s[6:7], s[6:7]
	v_mov_b64_e32 v[50:51], s[76:77]
	s_xor_b64 exec, exec, s[6:7]
	v_lshl_add_u32 v46, v87, 8, v88
	v_mov_b64_e32 v[50:51], s[12:13]
	s_or_b64 exec, exec, s[6:7]
	s_mov_b64 s[6:7], 0

; DI int crow(int i, int h) { return (i & 3) + 8 * (i >> 2) + 4 * h; }
; DI void phase_out(CP p, const Ptrs& w, int l, bf16_t* sA, bf16_t* sB) {
;     ...
;     for (int mi = 0; mi < 2; ++mi)
; #pragma unroll
;       for (int ni = 0; ni < 2; ++ni) {
;         int col = n0 + wn * 64 + ni * 32 + r;
;         float gt = gate[col];
; #pragma unroll
;         for (int i = 0; i < 16; ++i) {
;           int ii = ib + wm * 64 + mi * 32 + crow(i, h);
;           const float* src = xrow(p, w, l, b * TPB + ii);
;           float* dstp = isctx ? w.xc1 + (size_t)(b * CTXL + ii) * DM : p.out + (size_t)(b * 8192 + ii - CTXL) * DM;
;           dstp[col] = src[col] + gt * acc[mi][ni][i];
;         }
.LBB0_1519:
	v_ashrrev_i32_e32 v47, 31, v46
	v_lshlrev_b64 v[46:47], 13, v[46:47]
	v_lshl_add_u64 v[46:47], v[50:51], 0, v[46:47]
	v_lshl_add_u64 v[46:47], v[46:47], 0, v[66:67]
	v_add_u32_e32 v50, s39, v53
	v_ashrrev_i32_e32 v51, 31, v50
	v_lshlrev_b64 v[50:51], 13, v[50:51]
	v_lshl_add_u64 v[50:51], s[4:5], 0, v[50:51]
	v_lshl_add_u64 v[46:47], v[50:51], 0, v[66:67]
	s_mov_b64 s[6:7], -1
	s_and_b64 vcc, exec, s[40:41]
	s_waitcnt vmcnt(14)
	v_fma_f32 v53, v30, v58, v208
	v_or_b32_e32 v30, v52, v193
	v_add_u32_e32 v50, s38, v30
	v_mul_hi_i32 v51, v50, s0
	v_lshrrev_b32_e32 v52, 31, v51
	v_ashrrev_i32_e32 v51, 11, v51
	v_add_u32_e32 v89, v51, v52
	v_mad_i32_i24 v90, v89, s1, v50
	v_cmp_lt_i32_e64 s[72:73], s37, v90
	global_store_dword v[46:47], v53, off
	s_cbranch_vccnz .LBB0_1525
	s_and_saveexec_b64 s[6:7], s[72:73]
	s_xor_b64 s[6:7], exec, s[6:7]
	v_lshlrev_b32_e32 v50, 13, v89
	s_movk_i32 s10, 0xff00
	v_add3_u32 v50, v50, v90, s10
	s_or_saveexec_b64 s[6:7], s[6:7]
	v_mov_b64_e32 v[52:53], s[76:77]
	s_xor_b64 exec, exec, s[6:7]
	v_lshl_add_u32 v50, v89, 8, v90
	v_mov_b64_e32 v[52:53], s[12:13]
	s_or_b64 exec, exec, s[6:7]
	s_mov_b64 s[6:7], 0

; DI int crow(int i, int h) { return (i & 3) + 8 * (i >> 2) + 4 * h; }
; DI void phase_out(CP p, const Ptrs& w, int l, bf16_t* sA, bf16_t* sB) {
;     ...
;     for (int mi = 0; mi < 2; ++mi)
; #pragma unroll
;       for (int ni = 0; ni < 2; ++ni) {
;         int col = n0 + wn * 64 + ni * 32 + r;
;         float gt = gate[col];
; #pragma unroll
;         for (int i = 0; i < 16; ++i) {
;           int ii = ib + wm * 64 + mi * 32 + crow(i, h);
;           const float* src = xrow(p, w, l, b * TPB + ii);
;           float* dstp = isctx ? w.xc1 + (size_t)(b * CTXL + ii) * DM : p.out + (size_t)(b * 8192 + ii - CTXL) * DM;
;           dstp[col] = src[col] + gt * acc[mi][ni][i];
;         }
.LBB0_1531:
	v_ashrrev_i32_e32 v51, 31, v50
	v_lshlrev_b64 v[50:51], 13, v[50:51]
	v_lshl_add_u64 v[50:51], v[52:53], 0, v[50:51]
	v_lshl_add_u64 v[50:51], v[50:51], 0, v[66:67]
	v_add_u32_e32 v50, s39, v30
	v_ashrrev_i32_e32 v51, 31, v50
	v_lshlrev_b64 v[50:51], 13, v[50:51]
	v_lshl_add_u64 v[50:51], s[4:5], 0, v[50:51]
	s_and_b64 vcc, exec, s[40:41]
	s_mov_b64 s[4:5], -1
	s_waitcnt vmcnt(15)
	v_fma_f32 v52, v31, v58, v209
	v_lshl_add_u64 v[30:31], v[50:51], 0, v[66:67]
	global_store_dword v[30:31], v52, off
	global_load_dword v52, v[48:49], off
	s_cbranch_vccnz .LBB0_1537
	s_and_saveexec_b64 s[4:5], s[42:43]
	s_xor_b64 s[4:5], exec, s[4:5]
	v_lshlrev_b32_e32 v48, 13, v54
	s_movk_i32 s6, 0xff00
	v_add3_u32 v48, v48, v55, s6
	s_or_saveexec_b64 s[4:5], s[4:5]
	v_mov_b64_e32 v[50:51], s[76:77]
	s_xor_b64 exec, exec, s[4:5]
	v_lshl_add_u32 v48, v54, 8, v55
	v_mov_b64_e32 v[50:51], s[12:13]
	s_or_b64 exec, exec, s[4:5]
	s_mov_b64 s[4:5], 0

; DI int crow(int i, int h) { return (i & 3) + 8 * (i >> 2) + 4 * h; }
; DI void phase_out(CP p, const Ptrs& w, int l, bf16_t* sA, bf16_t* sB) {
;     ...
;     for (int mi = 0; mi < 2; ++mi)
; #pragma unroll
;       for (int ni = 0; ni < 2; ++ni) {
;         int col = n0 + wn * 64 + ni * 32 + r;
;         float gt = gate[col];
; #pragma unroll
;         for (int i = 0; i < 16; ++i) {
;           int ii = ib + wm * 64 + mi * 32 + crow(i, h);
;           const float* src = xrow(p, w, l, b * TPB + ii);
;           float* dstp = isctx ? w.xc1 + (size_t)(b * CTXL + ii) * DM : p.out + (size_t)(b * 8192 + ii - CTXL) * DM;
;           dstp[col] = src[col] + gt * acc[mi][ni][i];
;         }
.LBB0_1543:
	v_ashrrev_i32_e32 v49, 31, v48
	v_lshlrev_b64 v[48:49], 13, v[48:49]
	v_lshl_add_u64 v[48:49], v[50:51], 0, v[48:49]
	v_lshl_add_u64 v[48:49], v[64:65], 2, v[48:49]
	s_and_b64 vcc, exec, s[40:41]
	s_mov_b64 s[4:5], -1
	v_readlane_b32 s42, v255, 3
	s_waitcnt vmcnt(0)
	v_fma_f32 v48, v0, v52, v210
	global_store_dword v[32:33], v48, off offset:128
	s_cbranch_vccnz .LBB0_1549
	s_and_saveexec_b64 s[4:5], s[44:45]
	s_xor_b64 s[4:5], exec, s[4:5]
	v_lshlrev_b32_e32 v0, 13, v56
	s_movk_i32 s6, 0xff00
	v_add3_u32 v32, v0, v57, s6
	s_or_saveexec_b64 s[4:5], s[4:5]
	v_mov_b64_e32 v[48:49], s[76:77]
	s_xor_b64 exec, exec, s[4:5]
	v_lshl_add_u32 v32, v56, 8, v57
	v_mov_b64_e32 v[48:49], s[12:13]
	s_or_b64 exec, exec, s[4:5]
	s_mov_b64 s[4:5], 0

; DI int crow(int i, int h) { return (i & 3) + 8 * (i >> 2) + 4 * h; }
; DI void phase_out(CP p, const Ptrs& w, int l, bf16_t* sA, bf16_t* sB) {
;     ...
;     for (int mi = 0; mi < 2; ++mi)
; #pragma unroll
;       for (int ni = 0; ni < 2; ++ni) {
;         int col = n0 + wn * 64 + ni * 32 + r;
;         float gt = gate[col];
; #pragma unroll
;         for (int i = 0; i < 16; ++i) {
;           int ii = ib + wm * 64 + mi * 32 + crow(i, h);
;           const float* src = xrow(p, w, l, b * TPB + ii);
;           float* dstp = isctx ? w.xc1 + (size_t)(b * CTXL + ii) * DM : p.out + (size_t)(b * 8192 + ii - CTXL) * DM;
;           dstp[col] = src[col] + gt * acc[mi][ni][i];
;         }
.LBB0_1555:
	v_ashrrev_i32_e32 v33, 31, v32
	v_lshlrev_b64 v[32:33], 13, v[32:33]
	v_lshl_add_u64 v[32:33], v[48:49], 0, v[32:33]
	v_lshl_add_u64 v[32:33], v[64:65], 2, v[32:33]
	s_and_b64 vcc, exec, s[40:41]
	s_mov_b64 s[4:5], -1
	s_waitcnt vmcnt(1)
	v_fma_f32 v0, v1, v52, v211
	global_store_dword v[16:17], v0, off offset:128
	s_cbranch_vccnz .LBB0_1561
	s_and_saveexec_b64 s[4:5], s[46:47]
	s_xor_b64 s[4:5], exec, s[4:5]
	v_lshlrev_b32_e32 v0, 13, v59
	s_movk_i32 s6, 0xff00
	v_add3_u32 v0, v0, v60, s6
	s_or_saveexec_b64 s[4:5], s[4:5]
	v_mov_b64_e32 v[16:17], s[76:77]
	s_xor_b64 exec, exec, s[4:5]
	v_lshl_add_u32 v0, v59, 8, v60
	v_mov_b64_e32 v[16:17], s[12:13]
	s_or_b64 exec, exec, s[4:5]
	s_mov_b64 s[4:5], 0

; DI int crow(int i, int h) { return (i & 3) + 8 * (i >> 2) + 4 * h; }
; DI void phase_out(CP p, const Ptrs& w, int l, bf16_t* sA, bf16_t* sB) {
;     ...
;     for (int mi = 0; mi < 2; ++mi)
; #pragma unroll
;       for (int ni = 0; ni < 2; ++ni) {
;         int col = n0 + wn * 64 + ni * 32 + r;
;         float gt = gate[col];
; #pragma unroll
;         for (int i = 0; i < 16; ++i) {
;           int ii = ib + wm * 64 + mi * 32 + crow(i, h);
;           const float* src = xrow(p, w, l, b * TPB + ii);
;           float* dstp = isctx ? w.xc1 + (size_t)(b * CTXL + ii) * DM : p.out + (size_t)(b * 8192 + ii - CTXL) * DM;
;           dstp[col] = src[col] + gt * acc[mi][ni][i];
;         }
.LBB0_1567:
	v_ashrrev_i32_e32 v1, 31, v0
	v_lshlrev_b64 v[0:1], 13, v[0:1]
	v_lshl_add_u64 v[0:1], v[16:17], 0, v[0:1]
	v_lshl_add_u64 v[0:1], v[64:65], 2, v[0:1]
	s_and_b64 vcc, exec, s[40:41]
	s_mov_b64 s[4:5], -1
	s_waitcnt vmcnt(2)
	v_fma_f32 v0, v2, v52, v212
	global_store_dword v[34:35], v0, off offset:128
	s_cbranch_vccnz .LBB0_1573
	s_and_saveexec_b64 s[4:5], s[48:49]
	s_xor_b64 s[4:5], exec, s[4:5]
	v_lshlrev_b32_e32 v0, 13, v61
	s_movk_i32 s6, 0xff00
	v_add3_u32 v0, v0, v62, s6
	s_or_saveexec_b64 s[4:5], s[4:5]
	v_mov_b64_e32 v[16:17], s[76:77]
	s_xor_b64 exec, exec, s[4:5]
	v_lshl_add_u32 v0, v61, 8, v62
	v_mov_b64_e32 v[16:17], s[12:13]
	s_or_b64 exec, exec, s[4:5]
	s_mov_b64 s[4:5], 0

; DI int crow(int i, int h) { return (i & 3) + 8 * (i >> 2) + 4 * h; }
; DI void phase_out(CP p, const Ptrs& w, int l, bf16_t* sA, bf16_t* sB) {
;     ...
;     for (int mi = 0; mi < 2; ++mi)
; #pragma unroll
;       for (int ni = 0; ni < 2; ++ni) {
;         int col = n0 + wn * 64 + ni * 32 + r;
;         float gt = gate[col];
; #pragma unroll
;         for (int i = 0; i < 16; ++i) {
;           int ii = ib + wm * 64 + mi * 32 + crow(i, h);
;           const float* src = xrow(p, w, l, b * TPB + ii);
;           float* dstp = isctx ? w.xc1 + (size_t)(b * CTXL + ii) * DM : p.out + (size_t)(b * 8192 + ii - CTXL) * DM;
;           dstp[col] = src[col] + gt * acc[mi][ni][i];
;         }
.LBB0_1579:
	v_ashrrev_i32_e32 v1, 31, v0
	v_lshlrev_b64 v[0:1], 13, v[0:1]
	v_lshl_add_u64 v[0:1], v[16:17], 0, v[0:1]
	v_lshl_add_u64 v[0:1], v[64:65], 2, v[0:1]
	s_and_b64 vcc, exec, s[40:41]
	s_mov_b64 s[4:5], -1
	s_waitcnt vmcnt(3)
	v_fma_f32 v0, v3, v52, v213
	global_store_dword v[18:19], v0, off offset:128
	s_cbranch_vccnz .LBB0_1585
	s_and_saveexec_b64 s[4:5], s[50:51]
	s_xor_b64 s[4:5], exec, s[4:5]
	v_lshlrev_b32_e32 v0, 13, v63
	s_movk_i32 s6, 0xff00
	v_add3_u32 v0, v0, v68, s6
	s_or_saveexec_b64 s[4:5], s[4:5]
	v_mov_b64_e32 v[2:3], s[76:77]
	s_xor_b64 exec, exec, s[4:5]
	v_lshl_add_u32 v0, v63, 8, v68
	v_mov_b64_e32 v[2:3], s[12:13]
	s_or_b64 exec, exec, s[4:5]
	s_mov_b64 s[4:5], 0

; DI int crow(int i, int h) { return (i & 3) + 8 * (i >> 2) + 4 * h; }
; DI void phase_out(CP p, const Ptrs& w, int l, bf16_t* sA, bf16_t* sB) {
;     ...
;     for (int mi = 0; mi < 2; ++mi)
; #pragma unroll
;       for (int ni = 0; ni < 2; ++ni) {
;         int col = n0 + wn * 64 + ni * 32 + r;
;         float gt = gate[col];
; #pragma unroll
;         for (int i = 0; i < 16; ++i) {
;           int ii = ib + wm * 64 + mi * 32 + crow(i, h);
;           const float* src = xrow(p, w, l, b * TPB + ii);
;           float* dstp = isctx ? w.xc1 + (size_t)(b * CTXL + ii) * DM : p.out + (size_t)(b * 8192 + ii - CTXL) * DM;
;           dstp[col] = src[col] + gt * acc[mi][ni][i];
;         }
.LBB0_1591:
	v_ashrrev_i32_e32 v1, 31, v0
	v_lshlrev_b64 v[0:1], 13, v[0:1]
	v_lshl_add_u64 v[0:1], v[2:3], 0, v[0:1]
	v_lshl_add_u64 v[0:1], v[64:65], 2, v[0:1]
	s_and_b64 vcc, exec, s[40:41]
	s_mov_b64 s[4:5], -1
	s_waitcnt vmcnt(4)
	v_fma_f32 v0, v4, v52, v172
	global_store_dword v[36:37], v0, off offset:128
	s_cbranch_vccnz .LBB0_1597
	s_and_saveexec_b64 s[4:5], s[52:53]
	s_xor_b64 s[4:5], exec, s[4:5]
	v_lshlrev_b32_e32 v0, 13, v69
	s_movk_i32 s6, 0xff00
	v_add3_u32 v0, v0, v70, s6
	s_or_saveexec_b64 s[4:5], s[4:5]
	v_mov_b64_e32 v[2:3], s[76:77]
	s_xor_b64 exec, exec, s[4:5]
	v_lshl_add_u32 v0, v69, 8, v70
	v_mov_b64_e32 v[2:3], s[12:13]
	s_or_b64 exec, exec, s[4:5]
	s_mov_b64 s[4:5], 0

; DI int crow(int i, int h) { return (i & 3) + 8 * (i >> 2) + 4 * h; }
; DI void phase_out(CP p, const Ptrs& w, int l, bf16_t* sA, bf16_t* sB) {
;     ...
;     for (int mi = 0; mi < 2; ++mi)
; #pragma unroll
;       for (int ni = 0; ni < 2; ++ni) {
;         int col = n0 + wn * 64 + ni * 32 + r;
;         float gt = gate[col];
; #pragma unroll
;         for (int i = 0; i < 16; ++i) {
;           int ii = ib + wm * 64 + mi * 32 + crow(i, h);
;           const float* src = xrow(p, w, l, b * TPB + ii);
;           float* dstp = isctx ? w.xc1 + (size_t)(b * CTXL + ii) * DM : p.out + (size_t)(b * 8192 + ii - CTXL) * DM;
;           dstp[col] = src[col] + gt * acc[mi][ni][i];
;         }
.LBB0_1603:
	v_ashrrev_i32_e32 v1, 31, v0
	v_lshlrev_b64 v[0:1], 13, v[0:1]
	v_lshl_add_u64 v[0:1], v[2:3], 0, v[0:1]
	v_lshl_add_u64 v[0:1], v[64:65], 2, v[0:1]
	s_and_b64 vcc, exec, s[40:41]
	s_mov_b64 s[4:5], -1
	s_waitcnt vmcnt(5)
	v_fma_f32 v0, v5, v52, v173
	global_store_dword v[20:21], v0, off offset:128
	s_cbranch_vccnz .LBB0_1609
	s_and_saveexec_b64 s[4:5], s[54:55]
	s_xor_b64 s[4:5], exec, s[4:5]
	v_lshlrev_b32_e32 v0, 13, v71
	s_movk_i32 s6, 0xff00
	v_add3_u32 v0, v0, v72, s6
	s_or_saveexec_b64 s[4:5], s[4:5]
	v_mov_b64_e32 v[2:3], s[76:77]
	s_xor_b64 exec, exec, s[4:5]
	v_lshl_add_u32 v0, v71, 8, v72
	v_mov_b64_e32 v[2:3], s[12:13]
	s_or_b64 exec, exec, s[4:5]
	s_mov_b64 s[4:5], 0

; DI int crow(int i, int h) { return (i & 3) + 8 * (i >> 2) + 4 * h; }
; DI void phase_out(CP p, const Ptrs& w, int l, bf16_t* sA, bf16_t* sB) {
;     ...
;     for (int mi = 0; mi < 2; ++mi)
; #pragma unroll
;       for (int ni = 0; ni < 2; ++ni) {
;         int col = n0 + wn * 64 + ni * 32 + r;
;         float gt = gate[col];
; #pragma unroll
;         for (int i = 0; i < 16; ++i) {
;           int ii = ib + wm * 64 + mi * 32 + crow(i, h);
;           const float* src = xrow(p, w, l, b * TPB + ii);
;           float* dstp = isctx ? w.xc1 + (size_t)(b * CTXL + ii) * DM : p.out + (size_t)(b * 8192 + ii - CTXL) * DM;
;           dstp[col] = src[col] + gt * acc[mi][ni][i];
;         }
.LBB0_1615:
	v_ashrrev_i32_e32 v1, 31, v0
	v_lshlrev_b64 v[0:1], 13, v[0:1]
	v_lshl_add_u64 v[0:1], v[2:3], 0, v[0:1]
	v_lshl_add_u64 v[0:1], v[64:65], 2, v[0:1]
	s_and_b64 vcc, exec, s[40:41]
	s_mov_b64 s[4:5], -1
	s_waitcnt vmcnt(6)
	v_fma_f32 v0, v6, v52, v174
	global_store_dword v[38:39], v0, off offset:128
	s_cbranch_vccnz .LBB0_1621
	s_and_saveexec_b64 s[4:5], s[56:57]
	s_xor_b64 s[4:5], exec, s[4:5]
	v_lshlrev_b32_e32 v0, 13, v73
	s_movk_i32 s6, 0xff00
	v_add3_u32 v0, v0, v74, s6
	s_or_saveexec_b64 s[4:5], s[4:5]
	v_mov_b64_e32 v[2:3], s[76:77]
	s_xor_b64 exec, exec, s[4:5]
	v_lshl_add_u32 v0, v73, 8, v74
	v_mov_b64_e32 v[2:3], s[12:13]
	s_or_b64 exec, exec, s[4:5]
	s_mov_b64 s[4:5], 0

; DI int crow(int i, int h) { return (i & 3) + 8 * (i >> 2) + 4 * h; }
; DI void phase_out(CP p, const Ptrs& w, int l, bf16_t* sA, bf16_t* sB) {
;     ...
;     for (int mi = 0; mi < 2; ++mi)
; #pragma unroll
;       for (int ni = 0; ni < 2; ++ni) {
;         int col = n0 + wn * 64 + ni * 32 + r;
;         float gt = gate[col];
; #pragma unroll
;         for (int i = 0; i < 16; ++i) {
;           int ii = ib + wm * 64 + mi * 32 + crow(i, h);
;           const float* src = xrow(p, w, l, b * TPB + ii);
;           float* dstp = isctx ? w.xc1 + (size_t)(b * CTXL + ii) * DM : p.out + (size_t)(b * 8192 + ii - CTXL) * DM;
;           dstp[col] = src[col] + gt * acc[mi][ni][i];
;         }
.LBB0_1627:
	v_ashrrev_i32_e32 v1, 31, v0
	v_lshlrev_b64 v[0:1], 13, v[0:1]
	v_lshl_add_u64 v[0:1], v[2:3], 0, v[0:1]
	v_lshl_add_u64 v[0:1], v[64:65], 2, v[0:1]
	s_and_b64 vcc, exec, s[40:41]
	s_mov_b64 s[4:5], -1
	s_waitcnt vmcnt(7)
	v_fma_f32 v0, v7, v52, v175
	global_store_dword v[22:23], v0, off offset:128
	s_cbranch_vccnz .LBB0_1633
	s_and_saveexec_b64 s[4:5], s[58:59]
	s_xor_b64 s[4:5], exec, s[4:5]
	v_lshlrev_b32_e32 v0, 13, v75
	s_movk_i32 s6, 0xff00
	v_add3_u32 v0, v0, v76, s6
	s_or_saveexec_b64 s[4:5], s[4:5]
	v_mov_b64_e32 v[2:3], s[76:77]
	s_xor_b64 exec, exec, s[4:5]
	v_lshl_add_u32 v0, v75, 8, v76
	v_mov_b64_e32 v[2:3], s[12:13]
	s_or_b64 exec, exec, s[4:5]
	s_mov_b64 s[4:5], 0

; DI int crow(int i, int h) { return (i & 3) + 8 * (i >> 2) + 4 * h; }
; DI void phase_out(CP p, const Ptrs& w, int l, bf16_t* sA, bf16_t* sB) {
;     ...
;     for (int mi = 0; mi < 2; ++mi)
; #pragma unroll
;       for (int ni = 0; ni < 2; ++ni) {
;         int col = n0 + wn * 64 + ni * 32 + r;
;         float gt = gate[col];
; #pragma unroll
;         for (int i = 0; i < 16; ++i) {
;           int ii = ib + wm * 64 + mi * 32 + crow(i, h);
;           const float* src = xrow(p, w, l, b * TPB + ii);
;           float* dstp = isctx ? w.xc1 + (size_t)(b * CTXL + ii) * DM : p.out + (size_t)(b * 8192 + ii - CTXL) * DM;
;           dstp[col] = src[col] + gt * acc[mi][ni][i];
;         }
.LBB0_1639:
	v_ashrrev_i32_e32 v1, 31, v0
	v_lshlrev_b64 v[0:1], 13, v[0:1]
	v_lshl_add_u64 v[0:1], v[2:3], 0, v[0:1]
	v_lshl_add_u64 v[0:1], v[64:65], 2, v[0:1]
	s_and_b64 vcc, exec, s[40:41]
	s_mov_b64 s[4:5], -1
	s_waitcnt vmcnt(8)
	v_fma_f32 v0, v8, v52, v176
	global_store_dword v[40:41], v0, off offset:128
	s_cbranch_vccnz .LBB0_1645
	s_and_saveexec_b64 s[4:5], s[60:61]
	s_xor_b64 s[4:5], exec, s[4:5]
	v_lshlrev_b32_e32 v0, 13, v77
	s_movk_i32 s6, 0xff00
	v_add3_u32 v0, v0, v78, s6
	s_or_saveexec_b64 s[4:5], s[4:5]
	v_mov_b64_e32 v[2:3], s[76:77]
	s_xor_b64 exec, exec, s[4:5]
	v_lshl_add_u32 v0, v77, 8, v78
	v_mov_b64_e32 v[2:3], s[12:13]
	s_or_b64 exec, exec, s[4:5]
	s_mov_b64 s[4:5], 0

; DI int crow(int i, int h) { return (i & 3) + 8 * (i >> 2) + 4 * h; }
; DI void phase_out(CP p, const Ptrs& w, int l, bf16_t* sA, bf16_t* sB) {
;     ...
;     for (int mi = 0; mi < 2; ++mi)
; #pragma unroll
;       for (int ni = 0; ni < 2; ++ni) {
;         int col = n0 + wn * 64 + ni * 32 + r;
;         float gt = gate[col];
; #pragma unroll
;         for (int i = 0; i < 16; ++i) {
;           int ii = ib + wm * 64 + mi * 32 + crow(i, h);
;           const float* src = xrow(p, w, l, b * TPB + ii);
;           float* dstp = isctx ? w.xc1 + (size_t)(b * CTXL + ii) * DM : p.out + (size_t)(b * 8192 + ii - CTXL) * DM;
;           dstp[col] = src[col] + gt * acc[mi][ni][i];
;         }
.LBB0_1651:
	v_ashrrev_i32_e32 v1, 31, v0
	v_lshlrev_b64 v[0:1], 13, v[0:1]
	v_lshl_add_u64 v[0:1], v[2:3], 0, v[0:1]
	v_lshl_add_u64 v[0:1], v[64:65], 2, v[0:1]
	s_and_b64 vcc, exec, s[40:41]
	s_mov_b64 s[4:5], -1
	v_readlane_b32 s61, v254, 51
	s_waitcnt vmcnt(9)
	v_fma_f32 v0, v9, v52, v177
	global_store_dword v[24:25], v0, off offset:128
	s_cbranch_vccnz .LBB0_1657
	s_and_saveexec_b64 s[4:5], s[62:63]
	s_xor_b64 s[4:5], exec, s[4:5]
	v_lshlrev_b32_e32 v0, 13, v79
	s_movk_i32 s6, 0xff00
	v_add3_u32 v0, v0, v80, s6
	s_or_saveexec_b64 s[4:5], s[4:5]
	v_mov_b64_e32 v[2:3], s[76:77]
	s_xor_b64 exec, exec, s[4:5]
	v_lshl_add_u32 v0, v79, 8, v80
	v_mov_b64_e32 v[2:3], s[12:13]
	s_or_b64 exec, exec, s[4:5]
	s_mov_b64 s[4:5], 0

; DI int crow(int i, int h) { return (i & 3) + 8 * (i >> 2) + 4 * h; }
; DI void phase_out(CP p, const Ptrs& w, int l, bf16_t* sA, bf16_t* sB) {
;     ...
;     for (int mi = 0; mi < 2; ++mi)
; #pragma unroll
;       for (int ni = 0; ni < 2; ++ni) {
;         int col = n0 + wn * 64 + ni * 32 + r;
;         float gt = gate[col];
; #pragma unroll
;         for (int i = 0; i < 16; ++i) {
;           int ii = ib + wm * 64 + mi * 32 + crow(i, h);
;           const float* src = xrow(p, w, l, b * TPB + ii);
;           float* dstp = isctx ? w.xc1 + (size_t)(b * CTXL + ii) * DM : p.out + (size_t)(b * 8192 + ii - CTXL) * DM;
;           dstp[col] = src[col] + gt * acc[mi][ni][i];
;         }
.LBB0_1663:
	v_ashrrev_i32_e32 v1, 31, v0
	v_lshlrev_b64 v[0:1], 13, v[0:1]
	v_lshl_add_u64 v[0:1], v[2:3], 0, v[0:1]
	v_lshl_add_u64 v[0:1], v[64:65], 2, v[0:1]
	s_and_b64 vcc, exec, s[40:41]
	s_mov_b64 s[4:5], -1
	s_waitcnt vmcnt(10)
	v_fma_f32 v0, v10, v52, v178
	global_store_dword v[42:43], v0, off offset:128
	s_cbranch_vccnz .LBB0_1669
	s_and_saveexec_b64 s[4:5], s[64:65]
	s_xor_b64 s[4:5], exec, s[4:5]
	v_lshlrev_b32_e32 v0, 13, v81
	s_movk_i32 s6, 0xff00
	v_add3_u32 v0, v0, v82, s6
	s_or_saveexec_b64 s[4:5], s[4:5]
	v_mov_b64_e32 v[2:3], s[76:77]
	s_xor_b64 exec, exec, s[4:5]
	v_lshl_add_u32 v0, v81, 8, v82
	v_mov_b64_e32 v[2:3], s[12:13]
	s_or_b64 exec, exec, s[4:5]
	s_mov_b64 s[4:5], 0

; DI int crow(int i, int h) { return (i & 3) + 8 * (i >> 2) + 4 * h; }
; DI void phase_out(CP p, const Ptrs& w, int l, bf16_t* sA, bf16_t* sB) {
;     ...
;     for (int mi = 0; mi < 2; ++mi)
; #pragma unroll
;       for (int ni = 0; ni < 2; ++ni) {
;         int col = n0 + wn * 64 + ni * 32 + r;
;         float gt = gate[col];
; #pragma unroll
;         for (int i = 0; i < 16; ++i) {
;           int ii = ib + wm * 64 + mi * 32 + crow(i, h);
;           const float* src = xrow(p, w, l, b * TPB + ii);
;           float* dstp = isctx ? w.xc1 + (size_t)(b * CTXL + ii) * DM : p.out + (size_t)(b * 8192 + ii - CTXL) * DM;
;           dstp[col] = src[col] + gt * acc[mi][ni][i];
;         }
.LBB0_1675:
	v_ashrrev_i32_e32 v1, 31, v0
	v_lshlrev_b64 v[0:1], 13, v[0:1]
	v_lshl_add_u64 v[0:1], v[2:3], 0, v[0:1]
	v_lshl_add_u64 v[0:1], v[64:65], 2, v[0:1]
	s_and_b64 vcc, exec, s[40:41]
	s_mov_b64 s[4:5], -1
	s_waitcnt vmcnt(11)
	v_fma_f32 v0, v11, v52, v179
	global_store_dword v[26:27], v0, off offset:128
	s_cbranch_vccnz .LBB0_1681
	s_and_saveexec_b64 s[4:5], s[66:67]
	s_xor_b64 s[4:5], exec, s[4:5]
	v_lshlrev_b32_e32 v0, 13, v83
	s_movk_i32 s6, 0xff00
	v_add3_u32 v0, v0, v84, s6
	s_or_saveexec_b64 s[4:5], s[4:5]
	v_mov_b64_e32 v[2:3], s[76:77]
	s_xor_b64 exec, exec, s[4:5]
	v_lshl_add_u32 v0, v83, 8, v84
	v_mov_b64_e32 v[2:3], s[12:13]
	s_or_b64 exec, exec, s[4:5]
	s_mov_b64 s[4:5], 0

; DI int crow(int i, int h) { return (i & 3) + 8 * (i >> 2) + 4 * h; }
; DI void phase_out(CP p, const Ptrs& w, int l, bf16_t* sA, bf16_t* sB) {
;     ...
;     for (int mi = 0; mi < 2; ++mi)
; #pragma unroll
;       for (int ni = 0; ni < 2; ++ni) {
;         int col = n0 + wn * 64 + ni * 32 + r;
;         float gt = gate[col];
; #pragma unroll
;         for (int i = 0; i < 16; ++i) {
;           int ii = ib + wm * 64 + mi * 32 + crow(i, h);
;           const float* src = xrow(p, w, l, b * TPB + ii);
;           float* dstp = isctx ? w.xc1 + (size_t)(b * CTXL + ii) * DM : p.out + (size_t)(b * 8192 + ii - CTXL) * DM;
;           dstp[col] = src[col] + gt * acc[mi][ni][i];
;         }
.LBB0_1687:
	v_ashrrev_i32_e32 v1, 31, v0
	v_lshlrev_b64 v[0:1], 13, v[0:1]
	v_lshl_add_u64 v[0:1], v[2:3], 0, v[0:1]
	v_lshl_add_u64 v[0:1], v[64:65], 2, v[0:1]
	s_and_b64 vcc, exec, s[40:41]
	s_mov_b64 s[4:5], -1
	s_waitcnt vmcnt(12)
	v_fma_f32 v0, v12, v52, v132
	global_store_dword v[44:45], v0, off offset:128
	s_cbranch_vccnz .LBB0_1693
	s_and_saveexec_b64 s[4:5], s[68:69]
	s_xor_b64 s[4:5], exec, s[4:5]
	v_lshlrev_b32_e32 v0, 13, v85
	s_movk_i32 s6, 0xff00
	v_add3_u32 v0, v0, v86, s6
	s_or_saveexec_b64 s[4:5], s[4:5]
	v_mov_b64_e32 v[2:3], s[76:77]
	s_xor_b64 exec, exec, s[4:5]
	v_lshl_add_u32 v0, v85, 8, v86
	v_mov_b64_e32 v[2:3], s[12:13]
	s_or_b64 exec, exec, s[4:5]
	s_mov_b64 s[4:5], 0

; DI int crow(int i, int h) { return (i & 3) + 8 * (i >> 2) + 4 * h; }
; DI void phase_out(CP p, const Ptrs& w, int l, bf16_t* sA, bf16_t* sB) {
;     ...
;     for (int mi = 0; mi < 2; ++mi)
; #pragma unroll
;       for (int ni = 0; ni < 2; ++ni) {
;         int col = n0 + wn * 64 + ni * 32 + r;
;         float gt = gate[col];
; #pragma unroll
;         for (int i = 0; i < 16; ++i) {
;           int ii = ib + wm * 64 + mi * 32 + crow(i, h);
;           const float* src = xrow(p, w, l, b * TPB + ii);
;           float* dstp = isctx ? w.xc1 + (size_t)(b * CTXL + ii) * DM : p.out + (size_t)(b * 8192 + ii - CTXL) * DM;
;           dstp[col] = src[col] + gt * acc[mi][ni][i];
;         }
.LBB0_1699:
	v_ashrrev_i32_e32 v1, 31, v0
	v_lshlrev_b64 v[0:1], 13, v[0:1]
	v_lshl_add_u64 v[0:1], v[2:3], 0, v[0:1]
	v_lshl_add_u64 v[0:1], v[64:65], 2, v[0:1]
	s_and_b64 vcc, exec, s[40:41]
	s_mov_b64 s[4:5], -1
	s_waitcnt vmcnt(13)
	v_fma_f32 v0, v13, v52, v133
	global_store_dword v[28:29], v0, off offset:128
	s_cbranch_vccnz .LBB0_1705
	s_and_saveexec_b64 s[4:5], s[70:71]
	s_xor_b64 s[4:5], exec, s[4:5]
	v_lshlrev_b32_e32 v0, 13, v87
	s_movk_i32 s6, 0xff00
	v_add3_u32 v0, v0, v88, s6
	s_or_saveexec_b64 s[4:5], s[4:5]
	v_mov_b64_e32 v[2:3], s[76:77]
	s_xor_b64 exec, exec, s[4:5]
	v_lshl_add_u32 v0, v87, 8, v88
	v_mov_b64_e32 v[2:3], s[12:13]
	s_or_b64 exec, exec, s[4:5]
	s_mov_b64 s[4:5], 0

; DI int crow(int i, int h) { return (i & 3) + 8 * (i >> 2) + 4 * h; }
; DI void phase_out(CP p, const Ptrs& w, int l, bf16_t* sA, bf16_t* sB) {
;     ...
;     for (int mi = 0; mi < 2; ++mi)
; #pragma unroll
;       for (int ni = 0; ni < 2; ++ni) {
;         int col = n0 + wn * 64 + ni * 32 + r;
;         float gt = gate[col];
; #pragma unroll
;         for (int i = 0; i < 16; ++i) {
;           int ii = ib + wm * 64 + mi * 32 + crow(i, h);
;           const float* src = xrow(p, w, l, b * TPB + ii);
;           float* dstp = isctx ? w.xc1 + (size_t)(b * CTXL + ii) * DM : p.out + (size_t)(b * 8192 + ii - CTXL) * DM;
;           dstp[col] = src[col] + gt * acc[mi][ni][i];
;         }
.LBB0_1711:
	v_ashrrev_i32_e32 v1, 31, v0
	v_lshlrev_b64 v[0:1], 13, v[0:1]
	v_lshl_add_u64 v[0:1], v[2:3], 0, v[0:1]
	v_lshl_add_u64 v[0:1], v[64:65], 2, v[0:1]
	s_and_b64 vcc, exec, s[40:41]
	s_mov_b64 s[4:5], -1
	v_readlane_b32 s41, v255, 1
	s_waitcnt vmcnt(14)
	v_fma_f32 v0, v14, v52, v134
	global_store_dword v[46:47], v0, off offset:128
	s_cbranch_vccnz .LBB0_1717
	s_and_saveexec_b64 s[4:5], s[72:73]
	s_xor_b64 s[4:5], exec, s[4:5]
	v_lshlrev_b32_e32 v0, 13, v89
	s_movk_i32 s6, 0xff00
	v_add3_u32 v0, v0, v90, s6
	s_or_saveexec_b64 s[4:5], s[4:5]
	v_mov_b64_e32 v[2:3], s[76:77]
	s_xor_b64 exec, exec, s[4:5]
	v_lshl_add_u32 v0, v89, 8, v90
	v_mov_b64_e32 v[2:3], s[12:13]
	s_or_b64 exec, exec, s[4:5]
	s_mov_b64 s[4:5], 0
